# GEMM1 K-loop: deeper LDS-DMA pipeline (two 64-register fragment sets; DMA for K-step k+2 issued once step-k fragments are in registers)
# speedup vs baseline: 1.0105x; 1.0105x over previous
.LBB0_346:
	s_setprio 0
	v_and_b32_e32 v76, 63, v0
	v_lshrrev_b32_e32 v77, 6, v0
	v_and_b32_e32 v93, 15, v0
	v_readfirstlane_b32 s9, v77
	v_lshrrev_b32_e32 v78, 3, v76
	v_and_b32_e32 v79, 7, v76
	v_lshrrev_b32_e32 v80, 1, v78
	s_and_b32 s4, s9, 1
	s_lshl_b32 s4, s4, 2
	v_or_b32_e32 v80, s4, v80
	v_xor_b32_e32 v79, v79, v80
	s_lshl_b32 s4, s9, 3
	v_add_u32_e32 v78, s4, v78
	v_lshlrev_b32_e32 v78, 11, v78
	v_lshl_add_u32 v56, v79, 4, v78
	v_add_u32_e32 v57, 0x10000, v56
	v_add_u32_e32 v58, 0x20000, v56
	v_add_u32_e32 v59, 0x30000, v56
	s_lshl_b32 s4, s22, 18
	s_add_u32 s0, s48, s4
	s_addc_u32 s1, s49, 0
	s_lshl_b32 s4, s64, 18
	s_add_u32 s2, s44, s4
	s_addc_u32 s3, s45, 0
	s_lshl_b32 s4, s9, 10
	s_add_u32 s4, s4, 16
	v_bfe_u32 v2, v0, 4, 2
	v_bfe_u32 v81, v0, 1, 3
	v_xor_b32_e32 v82, v2, v81
	v_or_b32_e32 v83, 4, v2
	v_xor_b32_e32 v83, v83, v81
	v_lshlrev_b32_e32 v82, 4, v82
	v_lshlrev_b32_e32 v83, 4, v83
	v_lshlrev_b32_e32 v84, 7, v93
	v_ashrrev_i32_e32 v92, 7, v0
	s_lshr_b32 s9, s9, 1
	s_lshl_b32 s9, s9, 13
	v_add3_u32 v64, v84, s9, 16
	v_add_u32_e32 v65, v64, v83
	v_add_u32_e32 v64, v64, v82
	v_bfe_u32 v85, v0, 6, 1
	s_lshl_b32 s9, s64, 7
	v_lshl_or_b32 v94, v85, 6, s9
	v_lshlrev_b32_e32 v85, 13, v85
	v_add3_u32 v66, v84, v85, 16
	v_add_u32_e32 v66, 0x4000, v66
	v_add_u32_e32 v67, v66, v83
	v_add_u32_e32 v66, v66, v82
	v_mov_b32_e32 v60, 0
	v_mov_b32_e32 v61, 0
	v_mov_b32_e32 v62, 0
	v_mov_b32_e32 v63, 0
	v_mov_b32_e32 v68, 0
	v_mov_b32_e32 v69, 0
	v_mov_b32_e32 v70, 0
	v_mov_b32_e32 v71, 0
	v_mov_b32_e32 v52, 0
	v_mov_b32_e32 v53, 0
	v_mov_b32_e32 v54, 0
	v_mov_b32_e32 v55, 0
	v_mov_b32_e32 v40, 0
	v_mov_b32_e32 v41, 0
	v_mov_b32_e32 v42, 0
	v_mov_b32_e32 v43, 0
	v_mov_b32_e32 v72, 0
	v_mov_b32_e32 v73, 0
	v_mov_b32_e32 v74, 0
	v_mov_b32_e32 v75, 0
	v_mov_b32_e32 v48, 0
	v_mov_b32_e32 v49, 0
	v_mov_b32_e32 v50, 0
	v_mov_b32_e32 v51, 0
	v_mov_b32_e32 v44, 0
	v_mov_b32_e32 v45, 0
	v_mov_b32_e32 v46, 0
	v_mov_b32_e32 v47, 0
	v_mov_b32_e32 v36, 0
	v_mov_b32_e32 v37, 0
	v_mov_b32_e32 v38, 0
	v_mov_b32_e32 v39, 0
	v_mov_b32_e32 v32, 0
	v_mov_b32_e32 v33, 0
	v_mov_b32_e32 v34, 0
	v_mov_b32_e32 v35, 0
	v_mov_b32_e32 v28, 0
	v_mov_b32_e32 v29, 0
	v_mov_b32_e32 v30, 0
	v_mov_b32_e32 v31, 0
	v_mov_b32_e32 v24, 0
	v_mov_b32_e32 v25, 0
	v_mov_b32_e32 v26, 0
	v_mov_b32_e32 v27, 0
	v_mov_b32_e32 v20, 0
	v_mov_b32_e32 v21, 0
	v_mov_b32_e32 v22, 0
	v_mov_b32_e32 v23, 0
	v_mov_b32_e32 v16, 0
	v_mov_b32_e32 v17, 0
	v_mov_b32_e32 v18, 0
	v_mov_b32_e32 v19, 0
	v_mov_b32_e32 v12, 0
	v_mov_b32_e32 v13, 0
	v_mov_b32_e32 v14, 0
	v_mov_b32_e32 v15, 0
	v_mov_b32_e32 v8, 0
	v_mov_b32_e32 v9, 0
	v_mov_b32_e32 v10, 0
	v_mov_b32_e32 v11, 0
	v_mov_b32_e32 v4, 0
	v_mov_b32_e32 v5, 0
	v_mov_b32_e32 v6, 0
	v_mov_b32_e32 v7, 0
	s_cmp_eq_u32 s64, 24
	s_cbranch_scc1 .Lg1_narrow
	s_add_u32 m0, s4, 0x0
	s_nop 0
	global_load_lds_dwordx4 v56, s[0:1]
	s_add_u32 m0, s4, 0x1000
	s_nop 0
	global_load_lds_dwordx4 v57, s[0:1]
	s_add_u32 m0, s4, 0x2000
	s_nop 0
	global_load_lds_dwordx4 v58, s[0:1]
	s_add_u32 m0, s4, 0x3000
	s_nop 0
	global_load_lds_dwordx4 v59, s[0:1]
	s_add_u32 m0, s4, 0x4000
	s_nop 0
	global_load_lds_dwordx4 v56, s[2:3]
	s_add_u32 m0, s4, 0x5000
	s_nop 0
	global_load_lds_dwordx4 v57, s[2:3]
	s_add_u32 m0, s4, 0x6000
	s_nop 0
	global_load_lds_dwordx4 v58, s[2:3]
	s_add_u32 m0, s4, 0x7000
	s_nop 0
	global_load_lds_dwordx4 v59, s[2:3]
	s_add_u32 s0, s0, 0x80
	s_addc_u32 s1, s1, 0
	s_add_u32 s2, s2, 0x80
	s_addc_u32 s3, s3, 0
	s_add_u32 m0, s4, 0x8000
	s_nop 0
	global_load_lds_dwordx4 v56, s[0:1]
	s_add_u32 m0, s4, 0x9000
	s_nop 0
	global_load_lds_dwordx4 v57, s[0:1]
	s_add_u32 m0, s4, 0xa000
	s_nop 0
	global_load_lds_dwordx4 v58, s[0:1]
	s_add_u32 m0, s4, 0xb000
	s_nop 0
	global_load_lds_dwordx4 v59, s[0:1]
	s_add_u32 m0, s4, 0xc000
	s_nop 0
	global_load_lds_dwordx4 v56, s[2:3]
	s_add_u32 m0, s4, 0xd000
	s_nop 0
	global_load_lds_dwordx4 v57, s[2:3]
	s_add_u32 m0, s4, 0xe000
	s_nop 0
	global_load_lds_dwordx4 v58, s[2:3]
	s_add_u32 m0, s4, 0xf000
	s_nop 0
	global_load_lds_dwordx4 v59, s[2:3]
	s_add_u32 s0, s0, 0x80
	s_addc_u32 s1, s1, 0
	s_add_u32 s2, s2, 0x80
	s_addc_u32 s3, s3, 0
	s_waitcnt vmcnt(8)
	s_barrier
	ds_read_b128 v[140:143], v66 offset:0
	ds_read_b128 v[144:147], v66 offset:2048
	ds_read_b128 v[148:151], v66 offset:4096
	ds_read_b128 v[152:155], v66 offset:6144
	ds_read_b128 v[156:159], v64 offset:0
	ds_read_b128 v[160:163], v64 offset:2048
	ds_read_b128 v[164:167], v64 offset:4096
	ds_read_b128 v[168:171], v64 offset:6144
	ds_read_b128 v[172:175], v67 offset:0
	ds_read_b128 v[176:179], v67 offset:2048
	ds_read_b128 v[180:183], v67 offset:4096
	ds_read_b128 v[184:187], v67 offset:6144
	ds_read_b128 v[188:191], v65 offset:0
	ds_read_b128 v[192:195], v65 offset:2048
	ds_read_b128 v[196:199], v65 offset:4096
	ds_read_b128 v[200:203], v65 offset:6144
	s_waitcnt lgkmcnt(0)
	s_barrier
	v_mfma_f32_16x16x32_bf16 v[60:63], v[140:143], v[156:159], v[60:63]
	v_mfma_f32_16x16x32_bf16 v[68:71], v[140:143], v[160:163], v[68:71]
	s_add_u32 m0, s4, 0x0
	s_nop 0
	global_load_lds_dwordx4 v56, s[0:1]
	v_mfma_f32_16x16x32_bf16 v[52:55], v[140:143], v[164:167], v[52:55]
	v_mfma_f32_16x16x32_bf16 v[40:43], v[140:143], v[168:171], v[40:43]
	s_add_u32 m0, s4, 0x1000
	s_nop 0
	global_load_lds_dwordx4 v57, s[0:1]
	v_mfma_f32_16x16x32_bf16 v[72:75], v[144:147], v[156:159], v[72:75]
	v_mfma_f32_16x16x32_bf16 v[48:51], v[144:147], v[160:163], v[48:51]
	s_add_u32 m0, s4, 0x2000
	s_nop 0
	global_load_lds_dwordx4 v58, s[0:1]
	v_mfma_f32_16x16x32_bf16 v[44:47], v[144:147], v[164:167], v[44:47]
	v_mfma_f32_16x16x32_bf16 v[36:39], v[144:147], v[168:171], v[36:39]
	s_add_u32 m0, s4, 0x3000
	s_nop 0
	global_load_lds_dwordx4 v59, s[0:1]
	v_mfma_f32_16x16x32_bf16 v[32:35], v[148:151], v[156:159], v[32:35]
	v_mfma_f32_16x16x32_bf16 v[28:31], v[148:151], v[160:163], v[28:31]
	s_add_u32 m0, s4, 0x4000
	s_nop 0
	global_load_lds_dwordx4 v56, s[2:3]
	v_mfma_f32_16x16x32_bf16 v[24:27], v[148:151], v[164:167], v[24:27]
	v_mfma_f32_16x16x32_bf16 v[20:23], v[148:151], v[168:171], v[20:23]
	s_add_u32 m0, s4, 0x5000
	s_nop 0
	global_load_lds_dwordx4 v57, s[2:3]
	v_mfma_f32_16x16x32_bf16 v[16:19], v[152:155], v[156:159], v[16:19]
	v_mfma_f32_16x16x32_bf16 v[12:15], v[152:155], v[160:163], v[12:15]
	s_add_u32 m0, s4, 0x6000
	s_nop 0
	global_load_lds_dwordx4 v58, s[2:3]
	v_mfma_f32_16x16x32_bf16 v[8:11], v[152:155], v[164:167], v[8:11]
	v_mfma_f32_16x16x32_bf16 v[4:7], v[152:155], v[168:171], v[4:7]
	s_add_u32 m0, s4, 0x7000
	s_nop 0
	global_load_lds_dwordx4 v59, s[2:3]
	v_mfma_f32_16x16x32_bf16 v[60:63], v[172:175], v[188:191], v[60:63]
	v_mfma_f32_16x16x32_bf16 v[68:71], v[172:175], v[192:195], v[68:71]
	v_mfma_f32_16x16x32_bf16 v[52:55], v[172:175], v[196:199], v[52:55]
	v_mfma_f32_16x16x32_bf16 v[40:43], v[172:175], v[200:203], v[40:43]
	v_mfma_f32_16x16x32_bf16 v[72:75], v[176:179], v[188:191], v[72:75]
	v_mfma_f32_16x16x32_bf16 v[48:51], v[176:179], v[192:195], v[48:51]
	v_mfma_f32_16x16x32_bf16 v[44:47], v[176:179], v[196:199], v[44:47]
	v_mfma_f32_16x16x32_bf16 v[36:39], v[176:179], v[200:203], v[36:39]
	s_add_u32 s0, s0, 0x80
	s_addc_u32 s1, s1, 0
	s_add_u32 s2, s2, 0x80
	s_addc_u32 s3, s3, 0
	s_waitcnt vmcnt(8)
	s_barrier
	v_mfma_f32_16x16x32_bf16 v[32:35], v[180:183], v[188:191], v[32:35]
	ds_read_b128 v[220:223], v66 offset:32768
	ds_read_b128 v[224:227], v66 offset:34816
	v_mfma_f32_16x16x32_bf16 v[28:31], v[180:183], v[192:195], v[28:31]
	ds_read_b128 v[228:231], v66 offset:36864
	ds_read_b128 v[232:235], v66 offset:38912
	v_mfma_f32_16x16x32_bf16 v[24:27], v[180:183], v[196:199], v[24:27]
	ds_read_b128 v[236:239], v64 offset:32768
	ds_read_b128 v[240:243], v64 offset:34816
	v_mfma_f32_16x16x32_bf16 v[20:23], v[180:183], v[200:203], v[20:23]
	ds_read_b128 v[244:247], v64 offset:36864
	ds_read_b128 v[248:251], v64 offset:38912
	v_mfma_f32_16x16x32_bf16 v[16:19], v[184:187], v[188:191], v[16:19]
	ds_read_b128 v[112:115], v67 offset:32768
	ds_read_b128 v[116:119], v67 offset:34816
	v_mfma_f32_16x16x32_bf16 v[12:15], v[184:187], v[192:195], v[12:15]
	ds_read_b128 v[120:123], v67 offset:36864
	ds_read_b128 v[124:127], v67 offset:38912
	v_mfma_f32_16x16x32_bf16 v[8:11], v[184:187], v[196:199], v[8:11]
	ds_read_b128 v[76:79], v65 offset:32768
	ds_read_b128 v[80:83], v65 offset:34816
	v_mfma_f32_16x16x32_bf16 v[4:7], v[184:187], v[200:203], v[4:7]
	ds_read_b128 v[84:87], v65 offset:36864
	ds_read_b128 v[88:91], v65 offset:38912
	s_waitcnt lgkmcnt(0)
	s_barrier
	v_mfma_f32_16x16x32_bf16 v[60:63], v[220:223], v[236:239], v[60:63]
	v_mfma_f32_16x16x32_bf16 v[68:71], v[220:223], v[240:243], v[68:71]
	s_add_u32 m0, s4, 0x8000
	s_nop 0
	global_load_lds_dwordx4 v56, s[0:1]
	v_mfma_f32_16x16x32_bf16 v[52:55], v[220:223], v[244:247], v[52:55]
	v_mfma_f32_16x16x32_bf16 v[40:43], v[220:223], v[248:251], v[40:43]
	s_add_u32 m0, s4, 0x9000
	s_nop 0
	global_load_lds_dwordx4 v57, s[0:1]
	v_mfma_f32_16x16x32_bf16 v[72:75], v[224:227], v[236:239], v[72:75]
	v_mfma_f32_16x16x32_bf16 v[48:51], v[224:227], v[240:243], v[48:51]
	s_add_u32 m0, s4, 0xa000
	s_nop 0
	global_load_lds_dwordx4 v58, s[0:1]
	v_mfma_f32_16x16x32_bf16 v[44:47], v[224:227], v[244:247], v[44:47]
	v_mfma_f32_16x16x32_bf16 v[36:39], v[224:227], v[248:251], v[36:39]
	s_add_u32 m0, s4, 0xb000
	s_nop 0
	global_load_lds_dwordx4 v59, s[0:1]
	v_mfma_f32_16x16x32_bf16 v[32:35], v[228:231], v[236:239], v[32:35]
	v_mfma_f32_16x16x32_bf16 v[28:31], v[228:231], v[240:243], v[28:31]
	s_add_u32 m0, s4, 0xc000
	s_nop 0
	global_load_lds_dwordx4 v56, s[2:3]
	v_mfma_f32_16x16x32_bf16 v[24:27], v[228:231], v[244:247], v[24:27]
	v_mfma_f32_16x16x32_bf16 v[20:23], v[228:231], v[248:251], v[20:23]
	s_add_u32 m0, s4, 0xd000
	s_nop 0
	global_load_lds_dwordx4 v57, s[2:3]
	v_mfma_f32_16x16x32_bf16 v[16:19], v[232:235], v[236:239], v[16:19]
	v_mfma_f32_16x16x32_bf16 v[12:15], v[232:235], v[240:243], v[12:15]
	s_add_u32 m0, s4, 0xe000
	s_nop 0
	global_load_lds_dwordx4 v58, s[2:3]
	v_mfma_f32_16x16x32_bf16 v[8:11], v[232:235], v[244:247], v[8:11]
	v_mfma_f32_16x16x32_bf16 v[4:7], v[232:235], v[248:251], v[4:7]
	s_add_u32 m0, s4, 0xf000
	s_nop 0
	global_load_lds_dwordx4 v59, s[2:3]
	v_mfma_f32_16x16x32_bf16 v[60:63], v[112:115], v[76:79], v[60:63]
	v_mfma_f32_16x16x32_bf16 v[68:71], v[112:115], v[80:83], v[68:71]
	v_mfma_f32_16x16x32_bf16 v[52:55], v[112:115], v[84:87], v[52:55]
	v_mfma_f32_16x16x32_bf16 v[40:43], v[112:115], v[88:91], v[40:43]
	v_mfma_f32_16x16x32_bf16 v[72:75], v[116:119], v[76:79], v[72:75]
	v_mfma_f32_16x16x32_bf16 v[48:51], v[116:119], v[80:83], v[48:51]
	v_mfma_f32_16x16x32_bf16 v[44:47], v[116:119], v[84:87], v[44:47]
	v_mfma_f32_16x16x32_bf16 v[36:39], v[116:119], v[88:91], v[36:39]
	s_add_u32 s0, s0, 0x80
	s_addc_u32 s1, s1, 0
	s_add_u32 s2, s2, 0x80
	s_addc_u32 s3, s3, 0
	s_waitcnt vmcnt(8)
	s_barrier
	v_mfma_f32_16x16x32_bf16 v[32:35], v[120:123], v[76:79], v[32:35]
	ds_read_b128 v[140:143], v66 offset:0
	ds_read_b128 v[144:147], v66 offset:2048
	v_mfma_f32_16x16x32_bf16 v[28:31], v[120:123], v[80:83], v[28:31]
	ds_read_b128 v[148:151], v66 offset:4096
	ds_read_b128 v[152:155], v66 offset:6144
	v_mfma_f32_16x16x32_bf16 v[24:27], v[120:123], v[84:87], v[24:27]
	ds_read_b128 v[156:159], v64 offset:0
	ds_read_b128 v[160:163], v64 offset:2048
	v_mfma_f32_16x16x32_bf16 v[20:23], v[120:123], v[88:91], v[20:23]
	ds_read_b128 v[164:167], v64 offset:4096
	ds_read_b128 v[168:171], v64 offset:6144
	v_mfma_f32_16x16x32_bf16 v[16:19], v[124:127], v[76:79], v[16:19]
	ds_read_b128 v[172:175], v67 offset:0
	ds_read_b128 v[176:179], v67 offset:2048
	v_mfma_f32_16x16x32_bf16 v[12:15], v[124:127], v[80:83], v[12:15]
	ds_read_b128 v[180:183], v67 offset:4096
	ds_read_b128 v[184:187], v67 offset:6144
	v_mfma_f32_16x16x32_bf16 v[8:11], v[124:127], v[84:87], v[8:11]
	ds_read_b128 v[188:191], v65 offset:0
	ds_read_b128 v[192:195], v65 offset:2048
	v_mfma_f32_16x16x32_bf16 v[4:7], v[124:127], v[88:91], v[4:7]
	ds_read_b128 v[196:199], v65 offset:4096
	ds_read_b128 v[200:203], v65 offset:6144
	s_waitcnt lgkmcnt(0)
	s_barrier
	v_mfma_f32_16x16x32_bf16 v[60:63], v[140:143], v[156:159], v[60:63]
	v_mfma_f32_16x16x32_bf16 v[68:71], v[140:143], v[160:163], v[68:71]
	s_add_u32 m0, s4, 0x0
	s_nop 0
	global_load_lds_dwordx4 v56, s[0:1]
	v_mfma_f32_16x16x32_bf16 v[52:55], v[140:143], v[164:167], v[52:55]
	v_mfma_f32_16x16x32_bf16 v[40:43], v[140:143], v[168:171], v[40:43]
	s_add_u32 m0, s4, 0x1000
	s_nop 0
	global_load_lds_dwordx4 v57, s[0:1]
	v_mfma_f32_16x16x32_bf16 v[72:75], v[144:147], v[156:159], v[72:75]
	v_mfma_f32_16x16x32_bf16 v[48:51], v[144:147], v[160:163], v[48:51]
	s_add_u32 m0, s4, 0x2000
	s_nop 0
	global_load_lds_dwordx4 v58, s[0:1]
	v_mfma_f32_16x16x32_bf16 v[44:47], v[144:147], v[164:167], v[44:47]
	v_mfma_f32_16x16x32_bf16 v[36:39], v[144:147], v[168:171], v[36:39]
	s_add_u32 m0, s4, 0x3000
	s_nop 0
	global_load_lds_dwordx4 v59, s[0:1]
	v_mfma_f32_16x16x32_bf16 v[32:35], v[148:151], v[156:159], v[32:35]
	v_mfma_f32_16x16x32_bf16 v[28:31], v[148:151], v[160:163], v[28:31]
	s_add_u32 m0, s4, 0x4000
	s_nop 0
	global_load_lds_dwordx4 v56, s[2:3]
	v_mfma_f32_16x16x32_bf16 v[24:27], v[148:151], v[164:167], v[24:27]
	v_mfma_f32_16x16x32_bf16 v[20:23], v[148:151], v[168:171], v[20:23]
	s_add_u32 m0, s4, 0x5000
	s_nop 0
	global_load_lds_dwordx4 v57, s[2:3]
	v_mfma_f32_16x16x32_bf16 v[16:19], v[152:155], v[156:159], v[16:19]
	v_mfma_f32_16x16x32_bf16 v[12:15], v[152:155], v[160:163], v[12:15]
	s_add_u32 m0, s4, 0x6000
	s_nop 0
	global_load_lds_dwordx4 v58, s[2:3]
	v_mfma_f32_16x16x32_bf16 v[8:11], v[152:155], v[164:167], v[8:11]
	v_mfma_f32_16x16x32_bf16 v[4:7], v[152:155], v[168:171], v[4:7]
	s_add_u32 m0, s4, 0x7000
	s_nop 0
	global_load_lds_dwordx4 v59, s[2:3]
	v_mfma_f32_16x16x32_bf16 v[60:63], v[172:175], v[188:191], v[60:63]
	v_mfma_f32_16x16x32_bf16 v[68:71], v[172:175], v[192:195], v[68:71]
	v_mfma_f32_16x16x32_bf16 v[52:55], v[172:175], v[196:199], v[52:55]
	v_mfma_f32_16x16x32_bf16 v[40:43], v[172:175], v[200:203], v[40:43]
	v_mfma_f32_16x16x32_bf16 v[72:75], v[176:179], v[188:191], v[72:75]
	v_mfma_f32_16x16x32_bf16 v[48:51], v[176:179], v[192:195], v[48:51]
	v_mfma_f32_16x16x32_bf16 v[44:47], v[176:179], v[196:199], v[44:47]
	v_mfma_f32_16x16x32_bf16 v[36:39], v[176:179], v[200:203], v[36:39]
	s_add_u32 s0, s0, 0x80
	s_addc_u32 s1, s1, 0
	s_add_u32 s2, s2, 0x80
	s_addc_u32 s3, s3, 0
	s_waitcnt vmcnt(8)
	s_barrier
	v_mfma_f32_16x16x32_bf16 v[32:35], v[180:183], v[188:191], v[32:35]
	ds_read_b128 v[220:223], v66 offset:32768
	ds_read_b128 v[224:227], v66 offset:34816
	v_mfma_f32_16x16x32_bf16 v[28:31], v[180:183], v[192:195], v[28:31]
	ds_read_b128 v[228:231], v66 offset:36864
	ds_read_b128 v[232:235], v66 offset:38912
	v_mfma_f32_16x16x32_bf16 v[24:27], v[180:183], v[196:199], v[24:27]
	ds_read_b128 v[236:239], v64 offset:32768
	ds_read_b128 v[240:243], v64 offset:34816
	v_mfma_f32_16x16x32_bf16 v[20:23], v[180:183], v[200:203], v[20:23]
	ds_read_b128 v[244:247], v64 offset:36864
	ds_read_b128 v[248:251], v64 offset:38912
	v_mfma_f32_16x16x32_bf16 v[16:19], v[184:187], v[188:191], v[16:19]
	ds_read_b128 v[112:115], v67 offset:32768
	ds_read_b128 v[116:119], v67 offset:34816
	v_mfma_f32_16x16x32_bf16 v[12:15], v[184:187], v[192:195], v[12:15]
	ds_read_b128 v[120:123], v67 offset:36864
	ds_read_b128 v[124:127], v67 offset:38912
	v_mfma_f32_16x16x32_bf16 v[8:11], v[184:187], v[196:199], v[8:11]
	ds_read_b128 v[76:79], v65 offset:32768
	ds_read_b128 v[80:83], v65 offset:34816
	v_mfma_f32_16x16x32_bf16 v[4:7], v[184:187], v[200:203], v[4:7]
	ds_read_b128 v[84:87], v65 offset:36864
	ds_read_b128 v[88:91], v65 offset:38912
	s_waitcnt lgkmcnt(0)
	s_barrier
	v_mfma_f32_16x16x32_bf16 v[60:63], v[220:223], v[236:239], v[60:63]
	v_mfma_f32_16x16x32_bf16 v[68:71], v[220:223], v[240:243], v[68:71]
	s_add_u32 m0, s4, 0x8000
	s_nop 0
	global_load_lds_dwordx4 v56, s[0:1]
	v_mfma_f32_16x16x32_bf16 v[52:55], v[220:223], v[244:247], v[52:55]
	v_mfma_f32_16x16x32_bf16 v[40:43], v[220:223], v[248:251], v[40:43]
	s_add_u32 m0, s4, 0x9000
	s_nop 0
	global_load_lds_dwordx4 v57, s[0:1]
	v_mfma_f32_16x16x32_bf16 v[72:75], v[224:227], v[236:239], v[72:75]
	v_mfma_f32_16x16x32_bf16 v[48:51], v[224:227], v[240:243], v[48:51]
	s_add_u32 m0, s4, 0xa000
	s_nop 0
	global_load_lds_dwordx4 v58, s[0:1]
	v_mfma_f32_16x16x32_bf16 v[44:47], v[224:227], v[244:247], v[44:47]
	v_mfma_f32_16x16x32_bf16 v[36:39], v[224:227], v[248:251], v[36:39]
	s_add_u32 m0, s4, 0xb000
	s_nop 0
	global_load_lds_dwordx4 v59, s[0:1]
	v_mfma_f32_16x16x32_bf16 v[32:35], v[228:231], v[236:239], v[32:35]
	v_mfma_f32_16x16x32_bf16 v[28:31], v[228:231], v[240:243], v[28:31]
	s_add_u32 m0, s4, 0xc000
	s_nop 0
	global_load_lds_dwordx4 v56, s[2:3]
	v_mfma_f32_16x16x32_bf16 v[24:27], v[228:231], v[244:247], v[24:27]
	v_mfma_f32_16x16x32_bf16 v[20:23], v[228:231], v[248:251], v[20:23]
	s_add_u32 m0, s4, 0xd000
	s_nop 0
	global_load_lds_dwordx4 v57, s[2:3]
	v_mfma_f32_16x16x32_bf16 v[16:19], v[232:235], v[236:239], v[16:19]
	v_mfma_f32_16x16x32_bf16 v[12:15], v[232:235], v[240:243], v[12:15]
	s_add_u32 m0, s4, 0xe000
	s_nop 0
	global_load_lds_dwordx4 v58, s[2:3]
	v_mfma_f32_16x16x32_bf16 v[8:11], v[232:235], v[244:247], v[8:11]
	v_mfma_f32_16x16x32_bf16 v[4:7], v[232:235], v[248:251], v[4:7]
	s_add_u32 m0, s4, 0xf000
	s_nop 0
	global_load_lds_dwordx4 v59, s[2:3]
	v_mfma_f32_16x16x32_bf16 v[60:63], v[112:115], v[76:79], v[60:63]
	v_mfma_f32_16x16x32_bf16 v[68:71], v[112:115], v[80:83], v[68:71]
	v_mfma_f32_16x16x32_bf16 v[52:55], v[112:115], v[84:87], v[52:55]
	v_mfma_f32_16x16x32_bf16 v[40:43], v[112:115], v[88:91], v[40:43]
	v_mfma_f32_16x16x32_bf16 v[72:75], v[116:119], v[76:79], v[72:75]
	v_mfma_f32_16x16x32_bf16 v[48:51], v[116:119], v[80:83], v[48:51]
	v_mfma_f32_16x16x32_bf16 v[44:47], v[116:119], v[84:87], v[44:47]
	v_mfma_f32_16x16x32_bf16 v[36:39], v[116:119], v[88:91], v[36:39]
	s_add_u32 s0, s0, 0x80
	s_addc_u32 s1, s1, 0
	s_add_u32 s2, s2, 0x80
	s_addc_u32 s3, s3, 0
	s_waitcnt vmcnt(8)
	s_barrier
	v_mfma_f32_16x16x32_bf16 v[32:35], v[120:123], v[76:79], v[32:35]
	ds_read_b128 v[140:143], v66 offset:0
	ds_read_b128 v[144:147], v66 offset:2048
	v_mfma_f32_16x16x32_bf16 v[28:31], v[120:123], v[80:83], v[28:31]
	ds_read_b128 v[148:151], v66 offset:4096
	ds_read_b128 v[152:155], v66 offset:6144
	v_mfma_f32_16x16x32_bf16 v[24:27], v[120:123], v[84:87], v[24:27]
	ds_read_b128 v[156:159], v64 offset:0
	ds_read_b128 v[160:163], v64 offset:2048
	v_mfma_f32_16x16x32_bf16 v[20:23], v[120:123], v[88:91], v[20:23]
	ds_read_b128 v[164:167], v64 offset:4096
	ds_read_b128 v[168:171], v64 offset:6144
	v_mfma_f32_16x16x32_bf16 v[16:19], v[124:127], v[76:79], v[16:19]
	ds_read_b128 v[172:175], v67 offset:0
	ds_read_b128 v[176:179], v67 offset:2048
	v_mfma_f32_16x16x32_bf16 v[12:15], v[124:127], v[80:83], v[12:15]
	ds_read_b128 v[180:183], v67 offset:4096
	ds_read_b128 v[184:187], v67 offset:6144
	v_mfma_f32_16x16x32_bf16 v[8:11], v[124:127], v[84:87], v[8:11]
	ds_read_b128 v[188:191], v65 offset:0
	ds_read_b128 v[192:195], v65 offset:2048
	v_mfma_f32_16x16x32_bf16 v[4:7], v[124:127], v[88:91], v[4:7]
	ds_read_b128 v[196:199], v65 offset:4096
	ds_read_b128 v[200:203], v65 offset:6144
	s_waitcnt lgkmcnt(0)
	s_barrier
	v_mfma_f32_16x16x32_bf16 v[60:63], v[140:143], v[156:159], v[60:63]
	v_mfma_f32_16x16x32_bf16 v[68:71], v[140:143], v[160:163], v[68:71]
	s_add_u32 m0, s4, 0x0
	s_nop 0
	global_load_lds_dwordx4 v56, s[0:1]
	v_mfma_f32_16x16x32_bf16 v[52:55], v[140:143], v[164:167], v[52:55]
	v_mfma_f32_16x16x32_bf16 v[40:43], v[140:143], v[168:171], v[40:43]
	s_add_u32 m0, s4, 0x1000
	s_nop 0
	global_load_lds_dwordx4 v57, s[0:1]
	v_mfma_f32_16x16x32_bf16 v[72:75], v[144:147], v[156:159], v[72:75]
	v_mfma_f32_16x16x32_bf16 v[48:51], v[144:147], v[160:163], v[48:51]
	s_add_u32 m0, s4, 0x2000
	s_nop 0
	global_load_lds_dwordx4 v58, s[0:1]
	v_mfma_f32_16x16x32_bf16 v[44:47], v[144:147], v[164:167], v[44:47]
	v_mfma_f32_16x16x32_bf16 v[36:39], v[144:147], v[168:171], v[36:39]
	s_add_u32 m0, s4, 0x3000
	s_nop 0
	global_load_lds_dwordx4 v59, s[0:1]
	v_mfma_f32_16x16x32_bf16 v[32:35], v[148:151], v[156:159], v[32:35]
	v_mfma_f32_16x16x32_bf16 v[28:31], v[148:151], v[160:163], v[28:31]
	s_add_u32 m0, s4, 0x4000
	s_nop 0
	global_load_lds_dwordx4 v56, s[2:3]
	v_mfma_f32_16x16x32_bf16 v[24:27], v[148:151], v[164:167], v[24:27]
	v_mfma_f32_16x16x32_bf16 v[20:23], v[148:151], v[168:171], v[20:23]
	s_add_u32 m0, s4, 0x5000
	s_nop 0
	global_load_lds_dwordx4 v57, s[2:3]
	v_mfma_f32_16x16x32_bf16 v[16:19], v[152:155], v[156:159], v[16:19]
	v_mfma_f32_16x16x32_bf16 v[12:15], v[152:155], v[160:163], v[12:15]
	s_add_u32 m0, s4, 0x6000
	s_nop 0
	global_load_lds_dwordx4 v58, s[2:3]
	v_mfma_f32_16x16x32_bf16 v[8:11], v[152:155], v[164:167], v[8:11]
	v_mfma_f32_16x16x32_bf16 v[4:7], v[152:155], v[168:171], v[4:7]
	s_add_u32 m0, s4, 0x7000
	s_nop 0
	global_load_lds_dwordx4 v59, s[2:3]
	v_mfma_f32_16x16x32_bf16 v[60:63], v[172:175], v[188:191], v[60:63]
	v_mfma_f32_16x16x32_bf16 v[68:71], v[172:175], v[192:195], v[68:71]
	v_mfma_f32_16x16x32_bf16 v[52:55], v[172:175], v[196:199], v[52:55]
	v_mfma_f32_16x16x32_bf16 v[40:43], v[172:175], v[200:203], v[40:43]
	v_mfma_f32_16x16x32_bf16 v[72:75], v[176:179], v[188:191], v[72:75]
	v_mfma_f32_16x16x32_bf16 v[48:51], v[176:179], v[192:195], v[48:51]
	v_mfma_f32_16x16x32_bf16 v[44:47], v[176:179], v[196:199], v[44:47]
	v_mfma_f32_16x16x32_bf16 v[36:39], v[176:179], v[200:203], v[36:39]
	s_add_u32 s0, s0, 0x80
	s_addc_u32 s1, s1, 0
	s_add_u32 s2, s2, 0x80
	s_addc_u32 s3, s3, 0
	s_waitcnt vmcnt(8)
	s_barrier
	v_mfma_f32_16x16x32_bf16 v[32:35], v[180:183], v[188:191], v[32:35]
	ds_read_b128 v[220:223], v66 offset:32768
	ds_read_b128 v[224:227], v66 offset:34816
	v_mfma_f32_16x16x32_bf16 v[28:31], v[180:183], v[192:195], v[28:31]
	ds_read_b128 v[228:231], v66 offset:36864
	ds_read_b128 v[232:235], v66 offset:38912
	v_mfma_f32_16x16x32_bf16 v[24:27], v[180:183], v[196:199], v[24:27]
	ds_read_b128 v[236:239], v64 offset:32768
	ds_read_b128 v[240:243], v64 offset:34816
	v_mfma_f32_16x16x32_bf16 v[20:23], v[180:183], v[200:203], v[20:23]
	ds_read_b128 v[244:247], v64 offset:36864
	ds_read_b128 v[248:251], v64 offset:38912
	v_mfma_f32_16x16x32_bf16 v[16:19], v[184:187], v[188:191], v[16:19]
	ds_read_b128 v[112:115], v67 offset:32768
	ds_read_b128 v[116:119], v67 offset:34816
	v_mfma_f32_16x16x32_bf16 v[12:15], v[184:187], v[192:195], v[12:15]
	ds_read_b128 v[120:123], v67 offset:36864
	ds_read_b128 v[124:127], v67 offset:38912
	v_mfma_f32_16x16x32_bf16 v[8:11], v[184:187], v[196:199], v[8:11]
	ds_read_b128 v[76:79], v65 offset:32768
	ds_read_b128 v[80:83], v65 offset:34816
	v_mfma_f32_16x16x32_bf16 v[4:7], v[184:187], v[200:203], v[4:7]
	ds_read_b128 v[84:87], v65 offset:36864
	ds_read_b128 v[88:91], v65 offset:38912
	s_waitcnt lgkmcnt(0)
	s_barrier
	v_mfma_f32_16x16x32_bf16 v[60:63], v[220:223], v[236:239], v[60:63]
	v_mfma_f32_16x16x32_bf16 v[68:71], v[220:223], v[240:243], v[68:71]
	s_add_u32 m0, s4, 0x8000
	s_nop 0
	global_load_lds_dwordx4 v56, s[0:1]
	v_mfma_f32_16x16x32_bf16 v[52:55], v[220:223], v[244:247], v[52:55]
	v_mfma_f32_16x16x32_bf16 v[40:43], v[220:223], v[248:251], v[40:43]
	s_add_u32 m0, s4, 0x9000
	s_nop 0
	global_load_lds_dwordx4 v57, s[0:1]
	v_mfma_f32_16x16x32_bf16 v[72:75], v[224:227], v[236:239], v[72:75]
	v_mfma_f32_16x16x32_bf16 v[48:51], v[224:227], v[240:243], v[48:51]
	s_add_u32 m0, s4, 0xa000
	s_nop 0
	global_load_lds_dwordx4 v58, s[0:1]
	v_mfma_f32_16x16x32_bf16 v[44:47], v[224:227], v[244:247], v[44:47]
	v_mfma_f32_16x16x32_bf16 v[36:39], v[224:227], v[248:251], v[36:39]
	s_add_u32 m0, s4, 0xb000
	s_nop 0
	global_load_lds_dwordx4 v59, s[0:1]
	v_mfma_f32_16x16x32_bf16 v[32:35], v[228:231], v[236:239], v[32:35]
	v_mfma_f32_16x16x32_bf16 v[28:31], v[228:231], v[240:243], v[28:31]
	s_add_u32 m0, s4, 0xc000
	s_nop 0
	global_load_lds_dwordx4 v56, s[2:3]
	v_mfma_f32_16x16x32_bf16 v[24:27], v[228:231], v[244:247], v[24:27]
	v_mfma_f32_16x16x32_bf16 v[20:23], v[228:231], v[248:251], v[20:23]
	s_add_u32 m0, s4, 0xd000
	s_nop 0
	global_load_lds_dwordx4 v57, s[2:3]
	v_mfma_f32_16x16x32_bf16 v[16:19], v[232:235], v[236:239], v[16:19]
	v_mfma_f32_16x16x32_bf16 v[12:15], v[232:235], v[240:243], v[12:15]
	s_add_u32 m0, s4, 0xe000
	s_nop 0
	global_load_lds_dwordx4 v58, s[2:3]
	v_mfma_f32_16x16x32_bf16 v[8:11], v[232:235], v[244:247], v[8:11]
	v_mfma_f32_16x16x32_bf16 v[4:7], v[232:235], v[248:251], v[4:7]
	s_add_u32 m0, s4, 0xf000
	s_nop 0
	global_load_lds_dwordx4 v59, s[2:3]
	v_mfma_f32_16x16x32_bf16 v[60:63], v[112:115], v[76:79], v[60:63]
	v_mfma_f32_16x16x32_bf16 v[68:71], v[112:115], v[80:83], v[68:71]
	v_mfma_f32_16x16x32_bf16 v[52:55], v[112:115], v[84:87], v[52:55]
	v_mfma_f32_16x16x32_bf16 v[40:43], v[112:115], v[88:91], v[40:43]
	v_mfma_f32_16x16x32_bf16 v[72:75], v[116:119], v[76:79], v[72:75]
	v_mfma_f32_16x16x32_bf16 v[48:51], v[116:119], v[80:83], v[48:51]
	v_mfma_f32_16x16x32_bf16 v[44:47], v[116:119], v[84:87], v[44:47]
	v_mfma_f32_16x16x32_bf16 v[36:39], v[116:119], v[88:91], v[36:39]
	s_add_u32 s0, s0, 0x80
	s_addc_u32 s1, s1, 0
	s_add_u32 s2, s2, 0x80
	s_addc_u32 s3, s3, 0
	s_waitcnt vmcnt(8)
	s_barrier
	v_mfma_f32_16x16x32_bf16 v[32:35], v[120:123], v[76:79], v[32:35]
	ds_read_b128 v[140:143], v66 offset:0
	ds_read_b128 v[144:147], v66 offset:2048
	v_mfma_f32_16x16x32_bf16 v[28:31], v[120:123], v[80:83], v[28:31]
	ds_read_b128 v[148:151], v66 offset:4096
	ds_read_b128 v[152:155], v66 offset:6144
	v_mfma_f32_16x16x32_bf16 v[24:27], v[120:123], v[84:87], v[24:27]
	ds_read_b128 v[156:159], v64 offset:0
	ds_read_b128 v[160:163], v64 offset:2048
	v_mfma_f32_16x16x32_bf16 v[20:23], v[120:123], v[88:91], v[20:23]
	ds_read_b128 v[164:167], v64 offset:4096
	ds_read_b128 v[168:171], v64 offset:6144
	v_mfma_f32_16x16x32_bf16 v[16:19], v[124:127], v[76:79], v[16:19]
	ds_read_b128 v[172:175], v67 offset:0
	ds_read_b128 v[176:179], v67 offset:2048
	v_mfma_f32_16x16x32_bf16 v[12:15], v[124:127], v[80:83], v[12:15]
	ds_read_b128 v[180:183], v67 offset:4096
	ds_read_b128 v[184:187], v67 offset:6144
	v_mfma_f32_16x16x32_bf16 v[8:11], v[124:127], v[84:87], v[8:11]
	ds_read_b128 v[188:191], v65 offset:0
	ds_read_b128 v[192:195], v65 offset:2048
	v_mfma_f32_16x16x32_bf16 v[4:7], v[124:127], v[88:91], v[4:7]
	ds_read_b128 v[196:199], v65 offset:4096
	ds_read_b128 v[200:203], v65 offset:6144
	s_waitcnt lgkmcnt(0)
	s_barrier
	v_mfma_f32_16x16x32_bf16 v[60:63], v[140:143], v[156:159], v[60:63]
	v_mfma_f32_16x16x32_bf16 v[68:71], v[140:143], v[160:163], v[68:71]
	s_add_u32 m0, s4, 0x0
	s_nop 0
	global_load_lds_dwordx4 v56, s[0:1]
	v_mfma_f32_16x16x32_bf16 v[52:55], v[140:143], v[164:167], v[52:55]
	v_mfma_f32_16x16x32_bf16 v[40:43], v[140:143], v[168:171], v[40:43]
	s_add_u32 m0, s4, 0x1000
	s_nop 0
	global_load_lds_dwordx4 v57, s[0:1]
	v_mfma_f32_16x16x32_bf16 v[72:75], v[144:147], v[156:159], v[72:75]
	v_mfma_f32_16x16x32_bf16 v[48:51], v[144:147], v[160:163], v[48:51]
	s_add_u32 m0, s4, 0x2000
	s_nop 0
	global_load_lds_dwordx4 v58, s[0:1]
	v_mfma_f32_16x16x32_bf16 v[44:47], v[144:147], v[164:167], v[44:47]
	v_mfma_f32_16x16x32_bf16 v[36:39], v[144:147], v[168:171], v[36:39]
	s_add_u32 m0, s4, 0x3000
	s_nop 0
	global_load_lds_dwordx4 v59, s[0:1]
	v_mfma_f32_16x16x32_bf16 v[32:35], v[148:151], v[156:159], v[32:35]
	v_mfma_f32_16x16x32_bf16 v[28:31], v[148:151], v[160:163], v[28:31]
	s_add_u32 m0, s4, 0x4000
	s_nop 0
	global_load_lds_dwordx4 v56, s[2:3]
	v_mfma_f32_16x16x32_bf16 v[24:27], v[148:151], v[164:167], v[24:27]
	v_mfma_f32_16x16x32_bf16 v[20:23], v[148:151], v[168:171], v[20:23]
	s_add_u32 m0, s4, 0x5000
	s_nop 0
	global_load_lds_dwordx4 v57, s[2:3]
	v_mfma_f32_16x16x32_bf16 v[16:19], v[152:155], v[156:159], v[16:19]
	v_mfma_f32_16x16x32_bf16 v[12:15], v[152:155], v[160:163], v[12:15]
	s_add_u32 m0, s4, 0x6000
	s_nop 0
	global_load_lds_dwordx4 v58, s[2:3]
	v_mfma_f32_16x16x32_bf16 v[8:11], v[152:155], v[164:167], v[8:11]
	v_mfma_f32_16x16x32_bf16 v[4:7], v[152:155], v[168:171], v[4:7]
	s_add_u32 m0, s4, 0x7000
	s_nop 0
	global_load_lds_dwordx4 v59, s[2:3]
	v_mfma_f32_16x16x32_bf16 v[60:63], v[172:175], v[188:191], v[60:63]
	v_mfma_f32_16x16x32_bf16 v[68:71], v[172:175], v[192:195], v[68:71]
	v_mfma_f32_16x16x32_bf16 v[52:55], v[172:175], v[196:199], v[52:55]
	v_mfma_f32_16x16x32_bf16 v[40:43], v[172:175], v[200:203], v[40:43]
	v_mfma_f32_16x16x32_bf16 v[72:75], v[176:179], v[188:191], v[72:75]
	v_mfma_f32_16x16x32_bf16 v[48:51], v[176:179], v[192:195], v[48:51]
	v_mfma_f32_16x16x32_bf16 v[44:47], v[176:179], v[196:199], v[44:47]
	v_mfma_f32_16x16x32_bf16 v[36:39], v[176:179], v[200:203], v[36:39]
	s_add_u32 s0, s0, 0x80
	s_addc_u32 s1, s1, 0
	s_add_u32 s2, s2, 0x80
	s_addc_u32 s3, s3, 0
	s_waitcnt vmcnt(8)
	s_barrier
	v_mfma_f32_16x16x32_bf16 v[32:35], v[180:183], v[188:191], v[32:35]
	ds_read_b128 v[220:223], v66 offset:32768
	ds_read_b128 v[224:227], v66 offset:34816
	v_mfma_f32_16x16x32_bf16 v[28:31], v[180:183], v[192:195], v[28:31]
	ds_read_b128 v[228:231], v66 offset:36864
	ds_read_b128 v[232:235], v66 offset:38912
	v_mfma_f32_16x16x32_bf16 v[24:27], v[180:183], v[196:199], v[24:27]
	ds_read_b128 v[236:239], v64 offset:32768
	ds_read_b128 v[240:243], v64 offset:34816
	v_mfma_f32_16x16x32_bf16 v[20:23], v[180:183], v[200:203], v[20:23]
	ds_read_b128 v[244:247], v64 offset:36864
	ds_read_b128 v[248:251], v64 offset:38912
	v_mfma_f32_16x16x32_bf16 v[16:19], v[184:187], v[188:191], v[16:19]
	ds_read_b128 v[112:115], v67 offset:32768
	ds_read_b128 v[116:119], v67 offset:34816
	v_mfma_f32_16x16x32_bf16 v[12:15], v[184:187], v[192:195], v[12:15]
	ds_read_b128 v[120:123], v67 offset:36864
	ds_read_b128 v[124:127], v67 offset:38912
	v_mfma_f32_16x16x32_bf16 v[8:11], v[184:187], v[196:199], v[8:11]
	ds_read_b128 v[76:79], v65 offset:32768
	ds_read_b128 v[80:83], v65 offset:34816
	v_mfma_f32_16x16x32_bf16 v[4:7], v[184:187], v[200:203], v[4:7]
	ds_read_b128 v[84:87], v65 offset:36864
	ds_read_b128 v[88:91], v65 offset:38912
	s_waitcnt lgkmcnt(0)
	s_barrier
	v_mfma_f32_16x16x32_bf16 v[60:63], v[220:223], v[236:239], v[60:63]
	v_mfma_f32_16x16x32_bf16 v[68:71], v[220:223], v[240:243], v[68:71]
	s_add_u32 m0, s4, 0x8000
	s_nop 0
	global_load_lds_dwordx4 v56, s[0:1]
	v_mfma_f32_16x16x32_bf16 v[52:55], v[220:223], v[244:247], v[52:55]
	v_mfma_f32_16x16x32_bf16 v[40:43], v[220:223], v[248:251], v[40:43]
	s_add_u32 m0, s4, 0x9000
	s_nop 0
	global_load_lds_dwordx4 v57, s[0:1]
	v_mfma_f32_16x16x32_bf16 v[72:75], v[224:227], v[236:239], v[72:75]
	v_mfma_f32_16x16x32_bf16 v[48:51], v[224:227], v[240:243], v[48:51]
	s_add_u32 m0, s4, 0xa000
	s_nop 0
	global_load_lds_dwordx4 v58, s[0:1]
	v_mfma_f32_16x16x32_bf16 v[44:47], v[224:227], v[244:247], v[44:47]
	v_mfma_f32_16x16x32_bf16 v[36:39], v[224:227], v[248:251], v[36:39]
	s_add_u32 m0, s4, 0xb000
	s_nop 0
	global_load_lds_dwordx4 v59, s[0:1]
	v_mfma_f32_16x16x32_bf16 v[32:35], v[228:231], v[236:239], v[32:35]
	v_mfma_f32_16x16x32_bf16 v[28:31], v[228:231], v[240:243], v[28:31]
	s_add_u32 m0, s4, 0xc000
	s_nop 0
	global_load_lds_dwordx4 v56, s[2:3]
	v_mfma_f32_16x16x32_bf16 v[24:27], v[228:231], v[244:247], v[24:27]
	v_mfma_f32_16x16x32_bf16 v[20:23], v[228:231], v[248:251], v[20:23]
	s_add_u32 m0, s4, 0xd000
	s_nop 0
	global_load_lds_dwordx4 v57, s[2:3]
	v_mfma_f32_16x16x32_bf16 v[16:19], v[232:235], v[236:239], v[16:19]
	v_mfma_f32_16x16x32_bf16 v[12:15], v[232:235], v[240:243], v[12:15]
	s_add_u32 m0, s4, 0xe000
	s_nop 0
	global_load_lds_dwordx4 v58, s[2:3]
	v_mfma_f32_16x16x32_bf16 v[8:11], v[232:235], v[244:247], v[8:11]
	v_mfma_f32_16x16x32_bf16 v[4:7], v[232:235], v[248:251], v[4:7]
	s_add_u32 m0, s4, 0xf000
	s_nop 0
	global_load_lds_dwordx4 v59, s[2:3]
	v_mfma_f32_16x16x32_bf16 v[60:63], v[112:115], v[76:79], v[60:63]
	v_mfma_f32_16x16x32_bf16 v[68:71], v[112:115], v[80:83], v[68:71]
	v_mfma_f32_16x16x32_bf16 v[52:55], v[112:115], v[84:87], v[52:55]
	v_mfma_f32_16x16x32_bf16 v[40:43], v[112:115], v[88:91], v[40:43]
	v_mfma_f32_16x16x32_bf16 v[72:75], v[116:119], v[76:79], v[72:75]
	v_mfma_f32_16x16x32_bf16 v[48:51], v[116:119], v[80:83], v[48:51]
	v_mfma_f32_16x16x32_bf16 v[44:47], v[116:119], v[84:87], v[44:47]
	v_mfma_f32_16x16x32_bf16 v[36:39], v[116:119], v[88:91], v[36:39]
	s_add_u32 s0, s0, 0x80
	s_addc_u32 s1, s1, 0
	s_add_u32 s2, s2, 0x80
	s_addc_u32 s3, s3, 0
	s_waitcnt vmcnt(8)
	s_barrier
	v_mfma_f32_16x16x32_bf16 v[32:35], v[120:123], v[76:79], v[32:35]
	ds_read_b128 v[140:143], v66 offset:0
	ds_read_b128 v[144:147], v66 offset:2048
	v_mfma_f32_16x16x32_bf16 v[28:31], v[120:123], v[80:83], v[28:31]
	ds_read_b128 v[148:151], v66 offset:4096
	ds_read_b128 v[152:155], v66 offset:6144
	v_mfma_f32_16x16x32_bf16 v[24:27], v[120:123], v[84:87], v[24:27]
	ds_read_b128 v[156:159], v64 offset:0
	ds_read_b128 v[160:163], v64 offset:2048
	v_mfma_f32_16x16x32_bf16 v[20:23], v[120:123], v[88:91], v[20:23]
	ds_read_b128 v[164:167], v64 offset:4096
	ds_read_b128 v[168:171], v64 offset:6144
	v_mfma_f32_16x16x32_bf16 v[16:19], v[124:127], v[76:79], v[16:19]
	ds_read_b128 v[172:175], v67 offset:0
	ds_read_b128 v[176:179], v67 offset:2048
	v_mfma_f32_16x16x32_bf16 v[12:15], v[124:127], v[80:83], v[12:15]
	ds_read_b128 v[180:183], v67 offset:4096
	ds_read_b128 v[184:187], v67 offset:6144
	v_mfma_f32_16x16x32_bf16 v[8:11], v[124:127], v[84:87], v[8:11]
	ds_read_b128 v[188:191], v65 offset:0
	ds_read_b128 v[192:195], v65 offset:2048
	v_mfma_f32_16x16x32_bf16 v[4:7], v[124:127], v[88:91], v[4:7]
	ds_read_b128 v[196:199], v65 offset:4096
	ds_read_b128 v[200:203], v65 offset:6144
	s_waitcnt lgkmcnt(0)
	s_barrier
	v_mfma_f32_16x16x32_bf16 v[60:63], v[140:143], v[156:159], v[60:63]
	v_mfma_f32_16x16x32_bf16 v[68:71], v[140:143], v[160:163], v[68:71]
	s_add_u32 m0, s4, 0x0
	s_nop 0
	global_load_lds_dwordx4 v56, s[0:1]
	v_mfma_f32_16x16x32_bf16 v[52:55], v[140:143], v[164:167], v[52:55]
	v_mfma_f32_16x16x32_bf16 v[40:43], v[140:143], v[168:171], v[40:43]
	s_add_u32 m0, s4, 0x1000
	s_nop 0
	global_load_lds_dwordx4 v57, s[0:1]
	v_mfma_f32_16x16x32_bf16 v[72:75], v[144:147], v[156:159], v[72:75]
	v_mfma_f32_16x16x32_bf16 v[48:51], v[144:147], v[160:163], v[48:51]
	s_add_u32 m0, s4, 0x2000
	s_nop 0
	global_load_lds_dwordx4 v58, s[0:1]
	v_mfma_f32_16x16x32_bf16 v[44:47], v[144:147], v[164:167], v[44:47]
	v_mfma_f32_16x16x32_bf16 v[36:39], v[144:147], v[168:171], v[36:39]
	s_add_u32 m0, s4, 0x3000
	s_nop 0
	global_load_lds_dwordx4 v59, s[0:1]
	v_mfma_f32_16x16x32_bf16 v[32:35], v[148:151], v[156:159], v[32:35]
	v_mfma_f32_16x16x32_bf16 v[28:31], v[148:151], v[160:163], v[28:31]
	s_add_u32 m0, s4, 0x4000
	s_nop 0
	global_load_lds_dwordx4 v56, s[2:3]
	v_mfma_f32_16x16x32_bf16 v[24:27], v[148:151], v[164:167], v[24:27]
	v_mfma_f32_16x16x32_bf16 v[20:23], v[148:151], v[168:171], v[20:23]
	s_add_u32 m0, s4, 0x5000
	s_nop 0
	global_load_lds_dwordx4 v57, s[2:3]
	v_mfma_f32_16x16x32_bf16 v[16:19], v[152:155], v[156:159], v[16:19]
	v_mfma_f32_16x16x32_bf16 v[12:15], v[152:155], v[160:163], v[12:15]
	s_add_u32 m0, s4, 0x6000
	s_nop 0
	global_load_lds_dwordx4 v58, s[2:3]
	v_mfma_f32_16x16x32_bf16 v[8:11], v[152:155], v[164:167], v[8:11]
	v_mfma_f32_16x16x32_bf16 v[4:7], v[152:155], v[168:171], v[4:7]
	s_add_u32 m0, s4, 0x7000
	s_nop 0
	global_load_lds_dwordx4 v59, s[2:3]
	v_mfma_f32_16x16x32_bf16 v[60:63], v[172:175], v[188:191], v[60:63]
	v_mfma_f32_16x16x32_bf16 v[68:71], v[172:175], v[192:195], v[68:71]
	v_mfma_f32_16x16x32_bf16 v[52:55], v[172:175], v[196:199], v[52:55]
	v_mfma_f32_16x16x32_bf16 v[40:43], v[172:175], v[200:203], v[40:43]
	v_mfma_f32_16x16x32_bf16 v[72:75], v[176:179], v[188:191], v[72:75]
	v_mfma_f32_16x16x32_bf16 v[48:51], v[176:179], v[192:195], v[48:51]
	v_mfma_f32_16x16x32_bf16 v[44:47], v[176:179], v[196:199], v[44:47]
	v_mfma_f32_16x16x32_bf16 v[36:39], v[176:179], v[200:203], v[36:39]
	s_add_u32 s0, s0, 0x80
	s_addc_u32 s1, s1, 0
	s_add_u32 s2, s2, 0x80
	s_addc_u32 s3, s3, 0
	s_waitcnt vmcnt(8)
	s_barrier
	v_mfma_f32_16x16x32_bf16 v[32:35], v[180:183], v[188:191], v[32:35]
	ds_read_b128 v[220:223], v66 offset:32768
	ds_read_b128 v[224:227], v66 offset:34816
	v_mfma_f32_16x16x32_bf16 v[28:31], v[180:183], v[192:195], v[28:31]
	ds_read_b128 v[228:231], v66 offset:36864
	ds_read_b128 v[232:235], v66 offset:38912
	v_mfma_f32_16x16x32_bf16 v[24:27], v[180:183], v[196:199], v[24:27]
	ds_read_b128 v[236:239], v64 offset:32768
	ds_read_b128 v[240:243], v64 offset:34816
	v_mfma_f32_16x16x32_bf16 v[20:23], v[180:183], v[200:203], v[20:23]
	ds_read_b128 v[244:247], v64 offset:36864
	ds_read_b128 v[248:251], v64 offset:38912
	v_mfma_f32_16x16x32_bf16 v[16:19], v[184:187], v[188:191], v[16:19]
	ds_read_b128 v[112:115], v67 offset:32768
	ds_read_b128 v[116:119], v67 offset:34816
	v_mfma_f32_16x16x32_bf16 v[12:15], v[184:187], v[192:195], v[12:15]
	ds_read_b128 v[120:123], v67 offset:36864
	ds_read_b128 v[124:127], v67 offset:38912
	v_mfma_f32_16x16x32_bf16 v[8:11], v[184:187], v[196:199], v[8:11]
	ds_read_b128 v[76:79], v65 offset:32768
	ds_read_b128 v[80:83], v65 offset:34816
	v_mfma_f32_16x16x32_bf16 v[4:7], v[184:187], v[200:203], v[4:7]
	ds_read_b128 v[84:87], v65 offset:36864
	ds_read_b128 v[88:91], v65 offset:38912
	s_waitcnt lgkmcnt(0)
	s_barrier
	v_mfma_f32_16x16x32_bf16 v[60:63], v[220:223], v[236:239], v[60:63]
	v_mfma_f32_16x16x32_bf16 v[68:71], v[220:223], v[240:243], v[68:71]
	s_add_u32 m0, s4, 0x8000
	s_nop 0
	global_load_lds_dwordx4 v56, s[0:1]
	v_mfma_f32_16x16x32_bf16 v[52:55], v[220:223], v[244:247], v[52:55]
	v_mfma_f32_16x16x32_bf16 v[40:43], v[220:223], v[248:251], v[40:43]
	s_add_u32 m0, s4, 0x9000
	s_nop 0
	global_load_lds_dwordx4 v57, s[0:1]
	v_mfma_f32_16x16x32_bf16 v[72:75], v[224:227], v[236:239], v[72:75]
	v_mfma_f32_16x16x32_bf16 v[48:51], v[224:227], v[240:243], v[48:51]
	s_add_u32 m0, s4, 0xa000
	s_nop 0
	global_load_lds_dwordx4 v58, s[0:1]
	v_mfma_f32_16x16x32_bf16 v[44:47], v[224:227], v[244:247], v[44:47]
	v_mfma_f32_16x16x32_bf16 v[36:39], v[224:227], v[248:251], v[36:39]
	s_add_u32 m0, s4, 0xb000
	s_nop 0
	global_load_lds_dwordx4 v59, s[0:1]
	v_mfma_f32_16x16x32_bf16 v[32:35], v[228:231], v[236:239], v[32:35]
	v_mfma_f32_16x16x32_bf16 v[28:31], v[228:231], v[240:243], v[28:31]
	s_add_u32 m0, s4, 0xc000
	s_nop 0
	global_load_lds_dwordx4 v56, s[2:3]
	v_mfma_f32_16x16x32_bf16 v[24:27], v[228:231], v[244:247], v[24:27]
	v_mfma_f32_16x16x32_bf16 v[20:23], v[228:231], v[248:251], v[20:23]
	s_add_u32 m0, s4, 0xd000
	s_nop 0
	global_load_lds_dwordx4 v57, s[2:3]
	v_mfma_f32_16x16x32_bf16 v[16:19], v[232:235], v[236:239], v[16:19]
	v_mfma_f32_16x16x32_bf16 v[12:15], v[232:235], v[240:243], v[12:15]
	s_add_u32 m0, s4, 0xe000
	s_nop 0
	global_load_lds_dwordx4 v58, s[2:3]
	v_mfma_f32_16x16x32_bf16 v[8:11], v[232:235], v[244:247], v[8:11]
	v_mfma_f32_16x16x32_bf16 v[4:7], v[232:235], v[248:251], v[4:7]
	s_add_u32 m0, s4, 0xf000
	s_nop 0
	global_load_lds_dwordx4 v59, s[2:3]
	v_mfma_f32_16x16x32_bf16 v[60:63], v[112:115], v[76:79], v[60:63]
	v_mfma_f32_16x16x32_bf16 v[68:71], v[112:115], v[80:83], v[68:71]
	v_mfma_f32_16x16x32_bf16 v[52:55], v[112:115], v[84:87], v[52:55]
	v_mfma_f32_16x16x32_bf16 v[40:43], v[112:115], v[88:91], v[40:43]
	v_mfma_f32_16x16x32_bf16 v[72:75], v[116:119], v[76:79], v[72:75]
	v_mfma_f32_16x16x32_bf16 v[48:51], v[116:119], v[80:83], v[48:51]
	v_mfma_f32_16x16x32_bf16 v[44:47], v[116:119], v[84:87], v[44:47]
	v_mfma_f32_16x16x32_bf16 v[36:39], v[116:119], v[88:91], v[36:39]
	s_add_u32 s0, s0, 0x80
	s_addc_u32 s1, s1, 0
	s_add_u32 s2, s2, 0x80
	s_addc_u32 s3, s3, 0
	s_waitcnt vmcnt(8)
	s_barrier
	v_mfma_f32_16x16x32_bf16 v[32:35], v[120:123], v[76:79], v[32:35]
	ds_read_b128 v[140:143], v66 offset:0
	ds_read_b128 v[144:147], v66 offset:2048
	v_mfma_f32_16x16x32_bf16 v[28:31], v[120:123], v[80:83], v[28:31]
	ds_read_b128 v[148:151], v66 offset:4096
	ds_read_b128 v[152:155], v66 offset:6144
	v_mfma_f32_16x16x32_bf16 v[24:27], v[120:123], v[84:87], v[24:27]
	ds_read_b128 v[156:159], v64 offset:0
	ds_read_b128 v[160:163], v64 offset:2048
	v_mfma_f32_16x16x32_bf16 v[20:23], v[120:123], v[88:91], v[20:23]
	ds_read_b128 v[164:167], v64 offset:4096
	ds_read_b128 v[168:171], v64 offset:6144
	v_mfma_f32_16x16x32_bf16 v[16:19], v[124:127], v[76:79], v[16:19]
	ds_read_b128 v[172:175], v67 offset:0
	ds_read_b128 v[176:179], v67 offset:2048
	v_mfma_f32_16x16x32_bf16 v[12:15], v[124:127], v[80:83], v[12:15]
	ds_read_b128 v[180:183], v67 offset:4096
	ds_read_b128 v[184:187], v67 offset:6144
	v_mfma_f32_16x16x32_bf16 v[8:11], v[124:127], v[84:87], v[8:11]
	ds_read_b128 v[188:191], v65 offset:0
	ds_read_b128 v[192:195], v65 offset:2048
	v_mfma_f32_16x16x32_bf16 v[4:7], v[124:127], v[88:91], v[4:7]
	ds_read_b128 v[196:199], v65 offset:4096
	ds_read_b128 v[200:203], v65 offset:6144
	s_waitcnt lgkmcnt(0)
	s_barrier
	v_mfma_f32_16x16x32_bf16 v[60:63], v[140:143], v[156:159], v[60:63]
	v_mfma_f32_16x16x32_bf16 v[68:71], v[140:143], v[160:163], v[68:71]
	s_add_u32 m0, s4, 0x0
	s_nop 0
	global_load_lds_dwordx4 v56, s[0:1]
	v_mfma_f32_16x16x32_bf16 v[52:55], v[140:143], v[164:167], v[52:55]
	v_mfma_f32_16x16x32_bf16 v[40:43], v[140:143], v[168:171], v[40:43]
	s_add_u32 m0, s4, 0x1000
	s_nop 0
	global_load_lds_dwordx4 v57, s[0:1]
	v_mfma_f32_16x16x32_bf16 v[72:75], v[144:147], v[156:159], v[72:75]
	v_mfma_f32_16x16x32_bf16 v[48:51], v[144:147], v[160:163], v[48:51]
	s_add_u32 m0, s4, 0x2000
	s_nop 0
	global_load_lds_dwordx4 v58, s[0:1]
	v_mfma_f32_16x16x32_bf16 v[44:47], v[144:147], v[164:167], v[44:47]
	v_mfma_f32_16x16x32_bf16 v[36:39], v[144:147], v[168:171], v[36:39]
	s_add_u32 m0, s4, 0x3000
	s_nop 0
	global_load_lds_dwordx4 v59, s[0:1]
	v_mfma_f32_16x16x32_bf16 v[32:35], v[148:151], v[156:159], v[32:35]
	v_mfma_f32_16x16x32_bf16 v[28:31], v[148:151], v[160:163], v[28:31]
	s_add_u32 m0, s4, 0x4000
	s_nop 0
	global_load_lds_dwordx4 v56, s[2:3]
	v_mfma_f32_16x16x32_bf16 v[24:27], v[148:151], v[164:167], v[24:27]
	v_mfma_f32_16x16x32_bf16 v[20:23], v[148:151], v[168:171], v[20:23]
	s_add_u32 m0, s4, 0x5000
	s_nop 0
	global_load_lds_dwordx4 v57, s[2:3]
	v_mfma_f32_16x16x32_bf16 v[16:19], v[152:155], v[156:159], v[16:19]
	v_mfma_f32_16x16x32_bf16 v[12:15], v[152:155], v[160:163], v[12:15]
	s_add_u32 m0, s4, 0x6000
	s_nop 0
	global_load_lds_dwordx4 v58, s[2:3]
	v_mfma_f32_16x16x32_bf16 v[8:11], v[152:155], v[164:167], v[8:11]
	v_mfma_f32_16x16x32_bf16 v[4:7], v[152:155], v[168:171], v[4:7]
	s_add_u32 m0, s4, 0x7000
	s_nop 0
	global_load_lds_dwordx4 v59, s[2:3]
	v_mfma_f32_16x16x32_bf16 v[60:63], v[172:175], v[188:191], v[60:63]
	v_mfma_f32_16x16x32_bf16 v[68:71], v[172:175], v[192:195], v[68:71]
	v_mfma_f32_16x16x32_bf16 v[52:55], v[172:175], v[196:199], v[52:55]
	v_mfma_f32_16x16x32_bf16 v[40:43], v[172:175], v[200:203], v[40:43]
	v_mfma_f32_16x16x32_bf16 v[72:75], v[176:179], v[188:191], v[72:75]
	v_mfma_f32_16x16x32_bf16 v[48:51], v[176:179], v[192:195], v[48:51]
	v_mfma_f32_16x16x32_bf16 v[44:47], v[176:179], v[196:199], v[44:47]
	v_mfma_f32_16x16x32_bf16 v[36:39], v[176:179], v[200:203], v[36:39]
	s_add_u32 s0, s0, 0x80
	s_addc_u32 s1, s1, 0
	s_add_u32 s2, s2, 0x80
	s_addc_u32 s3, s3, 0
	s_waitcnt vmcnt(8)
	s_barrier
	v_mfma_f32_16x16x32_bf16 v[32:35], v[180:183], v[188:191], v[32:35]
	ds_read_b128 v[220:223], v66 offset:32768
	ds_read_b128 v[224:227], v66 offset:34816
	v_mfma_f32_16x16x32_bf16 v[28:31], v[180:183], v[192:195], v[28:31]
	ds_read_b128 v[228:231], v66 offset:36864
	ds_read_b128 v[232:235], v66 offset:38912
	v_mfma_f32_16x16x32_bf16 v[24:27], v[180:183], v[196:199], v[24:27]
	ds_read_b128 v[236:239], v64 offset:32768
	ds_read_b128 v[240:243], v64 offset:34816
	v_mfma_f32_16x16x32_bf16 v[20:23], v[180:183], v[200:203], v[20:23]
	ds_read_b128 v[244:247], v64 offset:36864
	ds_read_b128 v[248:251], v64 offset:38912
	v_mfma_f32_16x16x32_bf16 v[16:19], v[184:187], v[188:191], v[16:19]
	ds_read_b128 v[112:115], v67 offset:32768
	ds_read_b128 v[116:119], v67 offset:34816
	v_mfma_f32_16x16x32_bf16 v[12:15], v[184:187], v[192:195], v[12:15]
	ds_read_b128 v[120:123], v67 offset:36864
	ds_read_b128 v[124:127], v67 offset:38912
	v_mfma_f32_16x16x32_bf16 v[8:11], v[184:187], v[196:199], v[8:11]
	ds_read_b128 v[76:79], v65 offset:32768
	ds_read_b128 v[80:83], v65 offset:34816
	v_mfma_f32_16x16x32_bf16 v[4:7], v[184:187], v[200:203], v[4:7]
	ds_read_b128 v[84:87], v65 offset:36864
	ds_read_b128 v[88:91], v65 offset:38912
	s_waitcnt lgkmcnt(0)
	s_barrier
	v_mfma_f32_16x16x32_bf16 v[60:63], v[220:223], v[236:239], v[60:63]
	v_mfma_f32_16x16x32_bf16 v[68:71], v[220:223], v[240:243], v[68:71]
	s_add_u32 m0, s4, 0x8000
	s_nop 0
	global_load_lds_dwordx4 v56, s[0:1]
	v_mfma_f32_16x16x32_bf16 v[52:55], v[220:223], v[244:247], v[52:55]
	v_mfma_f32_16x16x32_bf16 v[40:43], v[220:223], v[248:251], v[40:43]
	s_add_u32 m0, s4, 0x9000
	s_nop 0
	global_load_lds_dwordx4 v57, s[0:1]
	v_mfma_f32_16x16x32_bf16 v[72:75], v[224:227], v[236:239], v[72:75]
	v_mfma_f32_16x16x32_bf16 v[48:51], v[224:227], v[240:243], v[48:51]
	s_add_u32 m0, s4, 0xa000
	s_nop 0
	global_load_lds_dwordx4 v58, s[0:1]
	v_mfma_f32_16x16x32_bf16 v[44:47], v[224:227], v[244:247], v[44:47]
	v_mfma_f32_16x16x32_bf16 v[36:39], v[224:227], v[248:251], v[36:39]
	s_add_u32 m0, s4, 0xb000
	s_nop 0
	global_load_lds_dwordx4 v59, s[0:1]
	v_mfma_f32_16x16x32_bf16 v[32:35], v[228:231], v[236:239], v[32:35]
	v_mfma_f32_16x16x32_bf16 v[28:31], v[228:231], v[240:243], v[28:31]
	s_add_u32 m0, s4, 0xc000
	s_nop 0
	global_load_lds_dwordx4 v56, s[2:3]
	v_mfma_f32_16x16x32_bf16 v[24:27], v[228:231], v[244:247], v[24:27]
	v_mfma_f32_16x16x32_bf16 v[20:23], v[228:231], v[248:251], v[20:23]
	s_add_u32 m0, s4, 0xd000
	s_nop 0
	global_load_lds_dwordx4 v57, s[2:3]
	v_mfma_f32_16x16x32_bf16 v[16:19], v[232:235], v[236:239], v[16:19]
	v_mfma_f32_16x16x32_bf16 v[12:15], v[232:235], v[240:243], v[12:15]
	s_add_u32 m0, s4, 0xe000
	s_nop 0
	global_load_lds_dwordx4 v58, s[2:3]
	v_mfma_f32_16x16x32_bf16 v[8:11], v[232:235], v[244:247], v[8:11]
	v_mfma_f32_16x16x32_bf16 v[4:7], v[232:235], v[248:251], v[4:7]
	s_add_u32 m0, s4, 0xf000
	s_nop 0
	global_load_lds_dwordx4 v59, s[2:3]
	v_mfma_f32_16x16x32_bf16 v[60:63], v[112:115], v[76:79], v[60:63]
	v_mfma_f32_16x16x32_bf16 v[68:71], v[112:115], v[80:83], v[68:71]
	v_mfma_f32_16x16x32_bf16 v[52:55], v[112:115], v[84:87], v[52:55]
	v_mfma_f32_16x16x32_bf16 v[40:43], v[112:115], v[88:91], v[40:43]
	v_mfma_f32_16x16x32_bf16 v[72:75], v[116:119], v[76:79], v[72:75]
	v_mfma_f32_16x16x32_bf16 v[48:51], v[116:119], v[80:83], v[48:51]
	v_mfma_f32_16x16x32_bf16 v[44:47], v[116:119], v[84:87], v[44:47]
	v_mfma_f32_16x16x32_bf16 v[36:39], v[116:119], v[88:91], v[36:39]
	s_add_u32 s0, s0, 0x80
	s_addc_u32 s1, s1, 0
	s_add_u32 s2, s2, 0x80
	s_addc_u32 s3, s3, 0
	s_waitcnt vmcnt(8)
	s_barrier
	v_mfma_f32_16x16x32_bf16 v[32:35], v[120:123], v[76:79], v[32:35]
	ds_read_b128 v[140:143], v66 offset:0
	ds_read_b128 v[144:147], v66 offset:2048
	v_mfma_f32_16x16x32_bf16 v[28:31], v[120:123], v[80:83], v[28:31]
	ds_read_b128 v[148:151], v66 offset:4096
	ds_read_b128 v[152:155], v66 offset:6144
	v_mfma_f32_16x16x32_bf16 v[24:27], v[120:123], v[84:87], v[24:27]
	ds_read_b128 v[156:159], v64 offset:0
	ds_read_b128 v[160:163], v64 offset:2048
	v_mfma_f32_16x16x32_bf16 v[20:23], v[120:123], v[88:91], v[20:23]
	ds_read_b128 v[164:167], v64 offset:4096
	ds_read_b128 v[168:171], v64 offset:6144
	v_mfma_f32_16x16x32_bf16 v[16:19], v[124:127], v[76:79], v[16:19]
	ds_read_b128 v[172:175], v67 offset:0
	ds_read_b128 v[176:179], v67 offset:2048
	v_mfma_f32_16x16x32_bf16 v[12:15], v[124:127], v[80:83], v[12:15]
	ds_read_b128 v[180:183], v67 offset:4096
	ds_read_b128 v[184:187], v67 offset:6144
	v_mfma_f32_16x16x32_bf16 v[8:11], v[124:127], v[84:87], v[8:11]
	ds_read_b128 v[188:191], v65 offset:0
	ds_read_b128 v[192:195], v65 offset:2048
	v_mfma_f32_16x16x32_bf16 v[4:7], v[124:127], v[88:91], v[4:7]
	ds_read_b128 v[196:199], v65 offset:4096
	ds_read_b128 v[200:203], v65 offset:6144
	s_waitcnt lgkmcnt(0)
	s_barrier
	v_mfma_f32_16x16x32_bf16 v[60:63], v[140:143], v[156:159], v[60:63]
	v_mfma_f32_16x16x32_bf16 v[68:71], v[140:143], v[160:163], v[68:71]
	s_add_u32 m0, s4, 0x0
	s_nop 0
	global_load_lds_dwordx4 v56, s[0:1]
	v_mfma_f32_16x16x32_bf16 v[52:55], v[140:143], v[164:167], v[52:55]
	v_mfma_f32_16x16x32_bf16 v[40:43], v[140:143], v[168:171], v[40:43]
	s_add_u32 m0, s4, 0x1000
	s_nop 0
	global_load_lds_dwordx4 v57, s[0:1]
	v_mfma_f32_16x16x32_bf16 v[72:75], v[144:147], v[156:159], v[72:75]
	v_mfma_f32_16x16x32_bf16 v[48:51], v[144:147], v[160:163], v[48:51]
	s_add_u32 m0, s4, 0x2000
	s_nop 0
	global_load_lds_dwordx4 v58, s[0:1]
	v_mfma_f32_16x16x32_bf16 v[44:47], v[144:147], v[164:167], v[44:47]
	v_mfma_f32_16x16x32_bf16 v[36:39], v[144:147], v[168:171], v[36:39]
	s_add_u32 m0, s4, 0x3000
	s_nop 0
	global_load_lds_dwordx4 v59, s[0:1]
	v_mfma_f32_16x16x32_bf16 v[32:35], v[148:151], v[156:159], v[32:35]
	v_mfma_f32_16x16x32_bf16 v[28:31], v[148:151], v[160:163], v[28:31]
	s_add_u32 m0, s4, 0x4000
	s_nop 0
	global_load_lds_dwordx4 v56, s[2:3]
	v_mfma_f32_16x16x32_bf16 v[24:27], v[148:151], v[164:167], v[24:27]
	v_mfma_f32_16x16x32_bf16 v[20:23], v[148:151], v[168:171], v[20:23]
	s_add_u32 m0, s4, 0x5000
	s_nop 0
	global_load_lds_dwordx4 v57, s[2:3]
	v_mfma_f32_16x16x32_bf16 v[16:19], v[152:155], v[156:159], v[16:19]
	v_mfma_f32_16x16x32_bf16 v[12:15], v[152:155], v[160:163], v[12:15]
	s_add_u32 m0, s4, 0x6000
	s_nop 0
	global_load_lds_dwordx4 v58, s[2:3]
	v_mfma_f32_16x16x32_bf16 v[8:11], v[152:155], v[164:167], v[8:11]
	v_mfma_f32_16x16x32_bf16 v[4:7], v[152:155], v[168:171], v[4:7]
	s_add_u32 m0, s4, 0x7000
	s_nop 0
	global_load_lds_dwordx4 v59, s[2:3]
	v_mfma_f32_16x16x32_bf16 v[60:63], v[172:175], v[188:191], v[60:63]
	v_mfma_f32_16x16x32_bf16 v[68:71], v[172:175], v[192:195], v[68:71]
	v_mfma_f32_16x16x32_bf16 v[52:55], v[172:175], v[196:199], v[52:55]
	v_mfma_f32_16x16x32_bf16 v[40:43], v[172:175], v[200:203], v[40:43]
	v_mfma_f32_16x16x32_bf16 v[72:75], v[176:179], v[188:191], v[72:75]
	v_mfma_f32_16x16x32_bf16 v[48:51], v[176:179], v[192:195], v[48:51]
	v_mfma_f32_16x16x32_bf16 v[44:47], v[176:179], v[196:199], v[44:47]
	v_mfma_f32_16x16x32_bf16 v[36:39], v[176:179], v[200:203], v[36:39]
	s_add_u32 s0, s0, 0x80
	s_addc_u32 s1, s1, 0
	s_add_u32 s2, s2, 0x80
	s_addc_u32 s3, s3, 0
	s_waitcnt vmcnt(8)
	s_barrier
	v_mfma_f32_16x16x32_bf16 v[32:35], v[180:183], v[188:191], v[32:35]
	ds_read_b128 v[220:223], v66 offset:32768
	ds_read_b128 v[224:227], v66 offset:34816
	v_mfma_f32_16x16x32_bf16 v[28:31], v[180:183], v[192:195], v[28:31]
	ds_read_b128 v[228:231], v66 offset:36864
	ds_read_b128 v[232:235], v66 offset:38912
	v_mfma_f32_16x16x32_bf16 v[24:27], v[180:183], v[196:199], v[24:27]
	ds_read_b128 v[236:239], v64 offset:32768
	ds_read_b128 v[240:243], v64 offset:34816
	v_mfma_f32_16x16x32_bf16 v[20:23], v[180:183], v[200:203], v[20:23]
	ds_read_b128 v[244:247], v64 offset:36864
	ds_read_b128 v[248:251], v64 offset:38912
	v_mfma_f32_16x16x32_bf16 v[16:19], v[184:187], v[188:191], v[16:19]
	ds_read_b128 v[112:115], v67 offset:32768
	ds_read_b128 v[116:119], v67 offset:34816
	v_mfma_f32_16x16x32_bf16 v[12:15], v[184:187], v[192:195], v[12:15]
	ds_read_b128 v[120:123], v67 offset:36864
	ds_read_b128 v[124:127], v67 offset:38912
	v_mfma_f32_16x16x32_bf16 v[8:11], v[184:187], v[196:199], v[8:11]
	ds_read_b128 v[76:79], v65 offset:32768
	ds_read_b128 v[80:83], v65 offset:34816
	v_mfma_f32_16x16x32_bf16 v[4:7], v[184:187], v[200:203], v[4:7]
	ds_read_b128 v[84:87], v65 offset:36864
	ds_read_b128 v[88:91], v65 offset:38912
	s_waitcnt lgkmcnt(0)
	s_barrier
	v_mfma_f32_16x16x32_bf16 v[60:63], v[220:223], v[236:239], v[60:63]
	v_mfma_f32_16x16x32_bf16 v[68:71], v[220:223], v[240:243], v[68:71]
	s_add_u32 m0, s4, 0x8000
	s_nop 0
	global_load_lds_dwordx4 v56, s[0:1]
	v_mfma_f32_16x16x32_bf16 v[52:55], v[220:223], v[244:247], v[52:55]
	v_mfma_f32_16x16x32_bf16 v[40:43], v[220:223], v[248:251], v[40:43]
	s_add_u32 m0, s4, 0x9000
	s_nop 0
	global_load_lds_dwordx4 v57, s[0:1]
	v_mfma_f32_16x16x32_bf16 v[72:75], v[224:227], v[236:239], v[72:75]
	v_mfma_f32_16x16x32_bf16 v[48:51], v[224:227], v[240:243], v[48:51]
	s_add_u32 m0, s4, 0xa000
	s_nop 0
	global_load_lds_dwordx4 v58, s[0:1]
	v_mfma_f32_16x16x32_bf16 v[44:47], v[224:227], v[244:247], v[44:47]
	v_mfma_f32_16x16x32_bf16 v[36:39], v[224:227], v[248:251], v[36:39]
	s_add_u32 m0, s4, 0xb000
	s_nop 0
	global_load_lds_dwordx4 v59, s[0:1]
	v_mfma_f32_16x16x32_bf16 v[32:35], v[228:231], v[236:239], v[32:35]
	v_mfma_f32_16x16x32_bf16 v[28:31], v[228:231], v[240:243], v[28:31]
	s_add_u32 m0, s4, 0xc000
	s_nop 0
	global_load_lds_dwordx4 v56, s[2:3]
	v_mfma_f32_16x16x32_bf16 v[24:27], v[228:231], v[244:247], v[24:27]
	v_mfma_f32_16x16x32_bf16 v[20:23], v[228:231], v[248:251], v[20:23]
	s_add_u32 m0, s4, 0xd000
	s_nop 0
	global_load_lds_dwordx4 v57, s[2:3]
	v_mfma_f32_16x16x32_bf16 v[16:19], v[232:235], v[236:239], v[16:19]
	v_mfma_f32_16x16x32_bf16 v[12:15], v[232:235], v[240:243], v[12:15]
	s_add_u32 m0, s4, 0xe000
	s_nop 0
	global_load_lds_dwordx4 v58, s[2:3]
	v_mfma_f32_16x16x32_bf16 v[8:11], v[232:235], v[244:247], v[8:11]
	v_mfma_f32_16x16x32_bf16 v[4:7], v[232:235], v[248:251], v[4:7]
	s_add_u32 m0, s4, 0xf000
	s_nop 0
	global_load_lds_dwordx4 v59, s[2:3]
	v_mfma_f32_16x16x32_bf16 v[60:63], v[112:115], v[76:79], v[60:63]
	v_mfma_f32_16x16x32_bf16 v[68:71], v[112:115], v[80:83], v[68:71]
	v_mfma_f32_16x16x32_bf16 v[52:55], v[112:115], v[84:87], v[52:55]
	v_mfma_f32_16x16x32_bf16 v[40:43], v[112:115], v[88:91], v[40:43]
	v_mfma_f32_16x16x32_bf16 v[72:75], v[116:119], v[76:79], v[72:75]
	v_mfma_f32_16x16x32_bf16 v[48:51], v[116:119], v[80:83], v[48:51]
	v_mfma_f32_16x16x32_bf16 v[44:47], v[116:119], v[84:87], v[44:47]
	v_mfma_f32_16x16x32_bf16 v[36:39], v[116:119], v[88:91], v[36:39]
	s_add_u32 s0, s0, 0x80
	s_addc_u32 s1, s1, 0
	s_add_u32 s2, s2, 0x80
	s_addc_u32 s3, s3, 0
	s_waitcnt vmcnt(8)
	s_barrier
	v_mfma_f32_16x16x32_bf16 v[32:35], v[120:123], v[76:79], v[32:35]
	ds_read_b128 v[140:143], v66 offset:0
	ds_read_b128 v[144:147], v66 offset:2048
	v_mfma_f32_16x16x32_bf16 v[28:31], v[120:123], v[80:83], v[28:31]
	ds_read_b128 v[148:151], v66 offset:4096
	ds_read_b128 v[152:155], v66 offset:6144
	v_mfma_f32_16x16x32_bf16 v[24:27], v[120:123], v[84:87], v[24:27]
	ds_read_b128 v[156:159], v64 offset:0
	ds_read_b128 v[160:163], v64 offset:2048
	v_mfma_f32_16x16x32_bf16 v[20:23], v[120:123], v[88:91], v[20:23]
	ds_read_b128 v[164:167], v64 offset:4096
	ds_read_b128 v[168:171], v64 offset:6144
	v_mfma_f32_16x16x32_bf16 v[16:19], v[124:127], v[76:79], v[16:19]
	ds_read_b128 v[172:175], v67 offset:0
	ds_read_b128 v[176:179], v67 offset:2048
	v_mfma_f32_16x16x32_bf16 v[12:15], v[124:127], v[80:83], v[12:15]
	ds_read_b128 v[180:183], v67 offset:4096
	ds_read_b128 v[184:187], v67 offset:6144
	v_mfma_f32_16x16x32_bf16 v[8:11], v[124:127], v[84:87], v[8:11]
	ds_read_b128 v[188:191], v65 offset:0
	ds_read_b128 v[192:195], v65 offset:2048
	v_mfma_f32_16x16x32_bf16 v[4:7], v[124:127], v[88:91], v[4:7]
	ds_read_b128 v[196:199], v65 offset:4096
	ds_read_b128 v[200:203], v65 offset:6144
	s_waitcnt lgkmcnt(0)
	s_barrier
	v_mfma_f32_16x16x32_bf16 v[60:63], v[140:143], v[156:159], v[60:63]
	v_mfma_f32_16x16x32_bf16 v[68:71], v[140:143], v[160:163], v[68:71]
	v_mfma_f32_16x16x32_bf16 v[52:55], v[140:143], v[164:167], v[52:55]
	v_mfma_f32_16x16x32_bf16 v[40:43], v[140:143], v[168:171], v[40:43]
	v_mfma_f32_16x16x32_bf16 v[72:75], v[144:147], v[156:159], v[72:75]
	v_mfma_f32_16x16x32_bf16 v[48:51], v[144:147], v[160:163], v[48:51]
	v_mfma_f32_16x16x32_bf16 v[44:47], v[144:147], v[164:167], v[44:47]
	v_mfma_f32_16x16x32_bf16 v[36:39], v[144:147], v[168:171], v[36:39]
	v_mfma_f32_16x16x32_bf16 v[32:35], v[148:151], v[156:159], v[32:35]
	v_mfma_f32_16x16x32_bf16 v[28:31], v[148:151], v[160:163], v[28:31]
	v_mfma_f32_16x16x32_bf16 v[24:27], v[148:151], v[164:167], v[24:27]
	v_mfma_f32_16x16x32_bf16 v[20:23], v[148:151], v[168:171], v[20:23]
	v_mfma_f32_16x16x32_bf16 v[16:19], v[152:155], v[156:159], v[16:19]
	v_mfma_f32_16x16x32_bf16 v[12:15], v[152:155], v[160:163], v[12:15]
	v_mfma_f32_16x16x32_bf16 v[8:11], v[152:155], v[164:167], v[8:11]
	v_mfma_f32_16x16x32_bf16 v[4:7], v[152:155], v[168:171], v[4:7]
	v_mfma_f32_16x16x32_bf16 v[60:63], v[172:175], v[188:191], v[60:63]
	v_mfma_f32_16x16x32_bf16 v[68:71], v[172:175], v[192:195], v[68:71]
	v_mfma_f32_16x16x32_bf16 v[52:55], v[172:175], v[196:199], v[52:55]
	v_mfma_f32_16x16x32_bf16 v[40:43], v[172:175], v[200:203], v[40:43]
	v_mfma_f32_16x16x32_bf16 v[72:75], v[176:179], v[188:191], v[72:75]
	v_mfma_f32_16x16x32_bf16 v[48:51], v[176:179], v[192:195], v[48:51]
	v_mfma_f32_16x16x32_bf16 v[44:47], v[176:179], v[196:199], v[44:47]
	v_mfma_f32_16x16x32_bf16 v[36:39], v[176:179], v[200:203], v[36:39]
	s_waitcnt vmcnt(0)
	s_barrier
	v_mfma_f32_16x16x32_bf16 v[32:35], v[180:183], v[188:191], v[32:35]
	ds_read_b128 v[220:223], v66 offset:32768
	ds_read_b128 v[224:227], v66 offset:34816
	v_mfma_f32_16x16x32_bf16 v[28:31], v[180:183], v[192:195], v[28:31]
	ds_read_b128 v[228:231], v66 offset:36864
	ds_read_b128 v[232:235], v66 offset:38912
	v_mfma_f32_16x16x32_bf16 v[24:27], v[180:183], v[196:199], v[24:27]
	ds_read_b128 v[236:239], v64 offset:32768
	ds_read_b128 v[240:243], v64 offset:34816
	v_mfma_f32_16x16x32_bf16 v[20:23], v[180:183], v[200:203], v[20:23]
	ds_read_b128 v[244:247], v64 offset:36864
	ds_read_b128 v[248:251], v64 offset:38912
	v_mfma_f32_16x16x32_bf16 v[16:19], v[184:187], v[188:191], v[16:19]
	ds_read_b128 v[112:115], v67 offset:32768
	ds_read_b128 v[116:119], v67 offset:34816
	v_mfma_f32_16x16x32_bf16 v[12:15], v[184:187], v[192:195], v[12:15]
	ds_read_b128 v[120:123], v67 offset:36864
	ds_read_b128 v[124:127], v67 offset:38912
	v_mfma_f32_16x16x32_bf16 v[8:11], v[184:187], v[196:199], v[8:11]
	ds_read_b128 v[76:79], v65 offset:32768
	ds_read_b128 v[80:83], v65 offset:34816
	v_mfma_f32_16x16x32_bf16 v[4:7], v[184:187], v[200:203], v[4:7]
	ds_read_b128 v[84:87], v65 offset:36864
	ds_read_b128 v[88:91], v65 offset:38912
	s_waitcnt lgkmcnt(0)
	s_barrier
	v_mfma_f32_16x16x32_bf16 v[60:63], v[220:223], v[236:239], v[60:63]
	v_mfma_f32_16x16x32_bf16 v[68:71], v[220:223], v[240:243], v[68:71]
	v_mfma_f32_16x16x32_bf16 v[52:55], v[220:223], v[244:247], v[52:55]
	v_mfma_f32_16x16x32_bf16 v[40:43], v[220:223], v[248:251], v[40:43]
	v_mfma_f32_16x16x32_bf16 v[72:75], v[224:227], v[236:239], v[72:75]
	v_mfma_f32_16x16x32_bf16 v[48:51], v[224:227], v[240:243], v[48:51]
	v_mfma_f32_16x16x32_bf16 v[44:47], v[224:227], v[244:247], v[44:47]
	v_mfma_f32_16x16x32_bf16 v[36:39], v[224:227], v[248:251], v[36:39]
	v_mfma_f32_16x16x32_bf16 v[32:35], v[228:231], v[236:239], v[32:35]
	v_mfma_f32_16x16x32_bf16 v[28:31], v[228:231], v[240:243], v[28:31]
	v_mfma_f32_16x16x32_bf16 v[24:27], v[228:231], v[244:247], v[24:27]
	v_mfma_f32_16x16x32_bf16 v[20:23], v[228:231], v[248:251], v[20:23]
	v_mfma_f32_16x16x32_bf16 v[16:19], v[232:235], v[236:239], v[16:19]
	v_mfma_f32_16x16x32_bf16 v[12:15], v[232:235], v[240:243], v[12:15]
	v_mfma_f32_16x16x32_bf16 v[8:11], v[232:235], v[244:247], v[8:11]
	v_mfma_f32_16x16x32_bf16 v[4:7], v[232:235], v[248:251], v[4:7]
	v_mfma_f32_16x16x32_bf16 v[60:63], v[112:115], v[76:79], v[60:63]
	v_mfma_f32_16x16x32_bf16 v[68:71], v[112:115], v[80:83], v[68:71]
	v_mfma_f32_16x16x32_bf16 v[52:55], v[112:115], v[84:87], v[52:55]
	v_mfma_f32_16x16x32_bf16 v[40:43], v[112:115], v[88:91], v[40:43]
	v_mfma_f32_16x16x32_bf16 v[72:75], v[116:119], v[76:79], v[72:75]
	v_mfma_f32_16x16x32_bf16 v[48:51], v[116:119], v[80:83], v[48:51]
	v_mfma_f32_16x16x32_bf16 v[44:47], v[116:119], v[84:87], v[44:47]
	v_mfma_f32_16x16x32_bf16 v[36:39], v[116:119], v[88:91], v[36:39]
	v_mfma_f32_16x16x32_bf16 v[32:35], v[120:123], v[76:79], v[32:35]
	v_mfma_f32_16x16x32_bf16 v[28:31], v[120:123], v[80:83], v[28:31]
	v_mfma_f32_16x16x32_bf16 v[24:27], v[120:123], v[84:87], v[24:27]
	v_mfma_f32_16x16x32_bf16 v[20:23], v[120:123], v[88:91], v[20:23]
	v_mfma_f32_16x16x32_bf16 v[16:19], v[124:127], v[76:79], v[16:19]
	v_mfma_f32_16x16x32_bf16 v[12:15], v[124:127], v[80:83], v[12:15]
	v_mfma_f32_16x16x32_bf16 v[8:11], v[124:127], v[84:87], v[8:11]
	v_mfma_f32_16x16x32_bf16 v[4:7], v[124:127], v[88:91], v[4:7]
	s_branch .Lg1_join
.Lg1_narrow:
	s_add_u32 m0, s4, 0x0
	s_nop 0
	global_load_lds_dwordx4 v56, s[0:1]
	s_add_u32 m0, s4, 0x1000
	s_nop 0
	global_load_lds_dwordx4 v57, s[0:1]
	s_add_u32 m0, s4, 0x2000
	s_nop 0
	global_load_lds_dwordx4 v58, s[0:1]
	s_add_u32 m0, s4, 0x3000
	s_nop 0
	global_load_lds_dwordx4 v59, s[0:1]
	s_add_u32 m0, s4, 0x4000
	s_nop 0
	global_load_lds_dwordx4 v56, s[2:3]
	s_add_u32 s0, s0, 0x80
	s_addc_u32 s1, s1, 0
	s_add_u32 s2, s2, 0x80
	s_addc_u32 s3, s3, 0
	s_add_u32 m0, s4, 0x8000
	s_nop 0
	global_load_lds_dwordx4 v56, s[0:1]
	s_add_u32 m0, s4, 0x9000
	s_nop 0
	global_load_lds_dwordx4 v57, s[0:1]
	s_add_u32 m0, s4, 0xa000
	s_nop 0
	global_load_lds_dwordx4 v58, s[0:1]
	s_add_u32 m0, s4, 0xb000
	s_nop 0
	global_load_lds_dwordx4 v59, s[0:1]
	s_add_u32 m0, s4, 0xc000
	s_nop 0
	global_load_lds_dwordx4 v56, s[2:3]
	s_add_u32 s0, s0, 0x80
	s_addc_u32 s1, s1, 0
	s_add_u32 s2, s2, 0x80
	s_addc_u32 s3, s3, 0
	s_waitcnt vmcnt(5)
	s_barrier
	ds_read_b128 v[140:143], v66 offset:0
	ds_read_b128 v[144:147], v66 offset:2048
	ds_read_b128 v[156:159], v64 offset:0
	ds_read_b128 v[160:163], v64 offset:2048
	ds_read_b128 v[164:167], v64 offset:4096
	ds_read_b128 v[168:171], v64 offset:6144
	ds_read_b128 v[172:175], v67 offset:0
	ds_read_b128 v[176:179], v67 offset:2048
	ds_read_b128 v[188:191], v65 offset:0
	ds_read_b128 v[192:195], v65 offset:2048
	ds_read_b128 v[196:199], v65 offset:4096
	ds_read_b128 v[200:203], v65 offset:6144
	s_waitcnt lgkmcnt(0)
	s_barrier
	v_mfma_f32_16x16x32_bf16 v[60:63], v[140:143], v[156:159], v[60:63]
	v_mfma_f32_16x16x32_bf16 v[68:71], v[140:143], v[160:163], v[68:71]
	s_add_u32 m0, s4, 0x0
	s_nop 0
	global_load_lds_dwordx4 v56, s[0:1]
	v_mfma_f32_16x16x32_bf16 v[52:55], v[140:143], v[164:167], v[52:55]
	v_mfma_f32_16x16x32_bf16 v[40:43], v[140:143], v[168:171], v[40:43]
	s_add_u32 m0, s4, 0x1000
	s_nop 0
	global_load_lds_dwordx4 v57, s[0:1]
	v_mfma_f32_16x16x32_bf16 v[72:75], v[144:147], v[156:159], v[72:75]
	v_mfma_f32_16x16x32_bf16 v[48:51], v[144:147], v[160:163], v[48:51]
	s_add_u32 m0, s4, 0x2000
	s_nop 0
	global_load_lds_dwordx4 v58, s[0:1]
	v_mfma_f32_16x16x32_bf16 v[44:47], v[144:147], v[164:167], v[44:47]
	v_mfma_f32_16x16x32_bf16 v[36:39], v[144:147], v[168:171], v[36:39]
	s_add_u32 m0, s4, 0x3000
	s_nop 0
	global_load_lds_dwordx4 v59, s[0:1]
	v_mfma_f32_16x16x32_bf16 v[60:63], v[172:175], v[188:191], v[60:63]
	v_mfma_f32_16x16x32_bf16 v[68:71], v[172:175], v[192:195], v[68:71]
	s_add_u32 m0, s4, 0x4000
	s_nop 0
	global_load_lds_dwordx4 v56, s[2:3]
	v_mfma_f32_16x16x32_bf16 v[52:55], v[172:175], v[196:199], v[52:55]
	v_mfma_f32_16x16x32_bf16 v[40:43], v[172:175], v[200:203], v[40:43]
	s_add_u32 s0, s0, 0x80
	s_addc_u32 s1, s1, 0
	s_add_u32 s2, s2, 0x80
	s_addc_u32 s3, s3, 0
	s_waitcnt vmcnt(5)
	s_barrier
	v_mfma_f32_16x16x32_bf16 v[72:75], v[176:179], v[188:191], v[72:75]
	ds_read_b128 v[220:223], v66 offset:32768
	ds_read_b128 v[224:227], v66 offset:34816
	ds_read_b128 v[236:239], v64 offset:32768
	v_mfma_f32_16x16x32_bf16 v[48:51], v[176:179], v[192:195], v[48:51]
	ds_read_b128 v[240:243], v64 offset:34816
	ds_read_b128 v[244:247], v64 offset:36864
	ds_read_b128 v[248:251], v64 offset:38912
	v_mfma_f32_16x16x32_bf16 v[44:47], v[176:179], v[196:199], v[44:47]
	ds_read_b128 v[112:115], v67 offset:32768
	ds_read_b128 v[116:119], v67 offset:34816
	ds_read_b128 v[76:79], v65 offset:32768
	v_mfma_f32_16x16x32_bf16 v[36:39], v[176:179], v[200:203], v[36:39]
	ds_read_b128 v[80:83], v65 offset:34816
	ds_read_b128 v[84:87], v65 offset:36864
	ds_read_b128 v[88:91], v65 offset:38912
	s_waitcnt lgkmcnt(0)
	s_barrier
	v_mfma_f32_16x16x32_bf16 v[60:63], v[220:223], v[236:239], v[60:63]
	v_mfma_f32_16x16x32_bf16 v[68:71], v[220:223], v[240:243], v[68:71]
	s_add_u32 m0, s4, 0x8000
	s_nop 0
	global_load_lds_dwordx4 v56, s[0:1]
	v_mfma_f32_16x16x32_bf16 v[52:55], v[220:223], v[244:247], v[52:55]
	v_mfma_f32_16x16x32_bf16 v[40:43], v[220:223], v[248:251], v[40:43]
	s_add_u32 m0, s4, 0x9000
	s_nop 0
	global_load_lds_dwordx4 v57, s[0:1]
	v_mfma_f32_16x16x32_bf16 v[72:75], v[224:227], v[236:239], v[72:75]
	v_mfma_f32_16x16x32_bf16 v[48:51], v[224:227], v[240:243], v[48:51]
	s_add_u32 m0, s4, 0xa000
	s_nop 0
	global_load_lds_dwordx4 v58, s[0:1]
	v_mfma_f32_16x16x32_bf16 v[44:47], v[224:227], v[244:247], v[44:47]
	v_mfma_f32_16x16x32_bf16 v[36:39], v[224:227], v[248:251], v[36:39]
	s_add_u32 m0, s4, 0xb000
	s_nop 0
	global_load_lds_dwordx4 v59, s[0:1]
	v_mfma_f32_16x16x32_bf16 v[60:63], v[112:115], v[76:79], v[60:63]
	v_mfma_f32_16x16x32_bf16 v[68:71], v[112:115], v[80:83], v[68:71]
	s_add_u32 m0, s4, 0xc000
	s_nop 0
	global_load_lds_dwordx4 v56, s[2:3]
	v_mfma_f32_16x16x32_bf16 v[52:55], v[112:115], v[84:87], v[52:55]
	v_mfma_f32_16x16x32_bf16 v[40:43], v[112:115], v[88:91], v[40:43]
	s_add_u32 s0, s0, 0x80
	s_addc_u32 s1, s1, 0
	s_add_u32 s2, s2, 0x80
	s_addc_u32 s3, s3, 0
	s_waitcnt vmcnt(5)
	s_barrier
	v_mfma_f32_16x16x32_bf16 v[72:75], v[116:119], v[76:79], v[72:75]
	ds_read_b128 v[140:143], v66 offset:0
	ds_read_b128 v[144:147], v66 offset:2048
	ds_read_b128 v[156:159], v64 offset:0
	v_mfma_f32_16x16x32_bf16 v[48:51], v[116:119], v[80:83], v[48:51]
	ds_read_b128 v[160:163], v64 offset:2048
	ds_read_b128 v[164:167], v64 offset:4096
	ds_read_b128 v[168:171], v64 offset:6144
	v_mfma_f32_16x16x32_bf16 v[44:47], v[116:119], v[84:87], v[44:47]
	ds_read_b128 v[172:175], v67 offset:0
	ds_read_b128 v[176:179], v67 offset:2048
	ds_read_b128 v[188:191], v65 offset:0
	v_mfma_f32_16x16x32_bf16 v[36:39], v[116:119], v[88:91], v[36:39]
	ds_read_b128 v[192:195], v65 offset:2048
	ds_read_b128 v[196:199], v65 offset:4096
	ds_read_b128 v[200:203], v65 offset:6144
	s_waitcnt lgkmcnt(0)
	s_barrier
	v_mfma_f32_16x16x32_bf16 v[60:63], v[140:143], v[156:159], v[60:63]
	v_mfma_f32_16x16x32_bf16 v[68:71], v[140:143], v[160:163], v[68:71]
	s_add_u32 m0, s4, 0x0
	s_nop 0
	global_load_lds_dwordx4 v56, s[0:1]
	v_mfma_f32_16x16x32_bf16 v[52:55], v[140:143], v[164:167], v[52:55]
	v_mfma_f32_16x16x32_bf16 v[40:43], v[140:143], v[168:171], v[40:43]
	s_add_u32 m0, s4, 0x1000
	s_nop 0
	global_load_lds_dwordx4 v57, s[0:1]
	v_mfma_f32_16x16x32_bf16 v[72:75], v[144:147], v[156:159], v[72:75]
	v_mfma_f32_16x16x32_bf16 v[48:51], v[144:147], v[160:163], v[48:51]
	s_add_u32 m0, s4, 0x2000
	s_nop 0
	global_load_lds_dwordx4 v58, s[0:1]
	v_mfma_f32_16x16x32_bf16 v[44:47], v[144:147], v[164:167], v[44:47]
	v_mfma_f32_16x16x32_bf16 v[36:39], v[144:147], v[168:171], v[36:39]
	s_add_u32 m0, s4, 0x3000
	s_nop 0
	global_load_lds_dwordx4 v59, s[0:1]
	v_mfma_f32_16x16x32_bf16 v[60:63], v[172:175], v[188:191], v[60:63]
	v_mfma_f32_16x16x32_bf16 v[68:71], v[172:175], v[192:195], v[68:71]
	s_add_u32 m0, s4, 0x4000
	s_nop 0
	global_load_lds_dwordx4 v56, s[2:3]
	v_mfma_f32_16x16x32_bf16 v[52:55], v[172:175], v[196:199], v[52:55]
	v_mfma_f32_16x16x32_bf16 v[40:43], v[172:175], v[200:203], v[40:43]
	s_add_u32 s0, s0, 0x80
	s_addc_u32 s1, s1, 0
	s_add_u32 s2, s2, 0x80
	s_addc_u32 s3, s3, 0
	s_waitcnt vmcnt(5)
	s_barrier
	v_mfma_f32_16x16x32_bf16 v[72:75], v[176:179], v[188:191], v[72:75]
	ds_read_b128 v[220:223], v66 offset:32768
	ds_read_b128 v[224:227], v66 offset:34816
	ds_read_b128 v[236:239], v64 offset:32768
	v_mfma_f32_16x16x32_bf16 v[48:51], v[176:179], v[192:195], v[48:51]
	ds_read_b128 v[240:243], v64 offset:34816
	ds_read_b128 v[244:247], v64 offset:36864
	ds_read_b128 v[248:251], v64 offset:38912
	v_mfma_f32_16x16x32_bf16 v[44:47], v[176:179], v[196:199], v[44:47]
	ds_read_b128 v[112:115], v67 offset:32768
	ds_read_b128 v[116:119], v67 offset:34816
	ds_read_b128 v[76:79], v65 offset:32768
	v_mfma_f32_16x16x32_bf16 v[36:39], v[176:179], v[200:203], v[36:39]
	ds_read_b128 v[80:83], v65 offset:34816
	ds_read_b128 v[84:87], v65 offset:36864
	ds_read_b128 v[88:91], v65 offset:38912
	s_waitcnt lgkmcnt(0)
	s_barrier
	v_mfma_f32_16x16x32_bf16 v[60:63], v[220:223], v[236:239], v[60:63]
	v_mfma_f32_16x16x32_bf16 v[68:71], v[220:223], v[240:243], v[68:71]
	s_add_u32 m0, s4, 0x8000
	s_nop 0
	global_load_lds_dwordx4 v56, s[0:1]
	v_mfma_f32_16x16x32_bf16 v[52:55], v[220:223], v[244:247], v[52:55]
	v_mfma_f32_16x16x32_bf16 v[40:43], v[220:223], v[248:251], v[40:43]
	s_add_u32 m0, s4, 0x9000
	s_nop 0
	global_load_lds_dwordx4 v57, s[0:1]
	v_mfma_f32_16x16x32_bf16 v[72:75], v[224:227], v[236:239], v[72:75]
	v_mfma_f32_16x16x32_bf16 v[48:51], v[224:227], v[240:243], v[48:51]
	s_add_u32 m0, s4, 0xa000
	s_nop 0
	global_load_lds_dwordx4 v58, s[0:1]
	v_mfma_f32_16x16x32_bf16 v[44:47], v[224:227], v[244:247], v[44:47]
	v_mfma_f32_16x16x32_bf16 v[36:39], v[224:227], v[248:251], v[36:39]
	s_add_u32 m0, s4, 0xb000
	s_nop 0
	global_load_lds_dwordx4 v59, s[0:1]
	v_mfma_f32_16x16x32_bf16 v[60:63], v[112:115], v[76:79], v[60:63]
	v_mfma_f32_16x16x32_bf16 v[68:71], v[112:115], v[80:83], v[68:71]
	s_add_u32 m0, s4, 0xc000
	s_nop 0
	global_load_lds_dwordx4 v56, s[2:3]
	v_mfma_f32_16x16x32_bf16 v[52:55], v[112:115], v[84:87], v[52:55]
	v_mfma_f32_16x16x32_bf16 v[40:43], v[112:115], v[88:91], v[40:43]
	s_add_u32 s0, s0, 0x80
	s_addc_u32 s1, s1, 0
	s_add_u32 s2, s2, 0x80
	s_addc_u32 s3, s3, 0
	s_waitcnt vmcnt(5)
	s_barrier
	v_mfma_f32_16x16x32_bf16 v[72:75], v[116:119], v[76:79], v[72:75]
	ds_read_b128 v[140:143], v66 offset:0
	ds_read_b128 v[144:147], v66 offset:2048
	ds_read_b128 v[156:159], v64 offset:0
	v_mfma_f32_16x16x32_bf16 v[48:51], v[116:119], v[80:83], v[48:51]
	ds_read_b128 v[160:163], v64 offset:2048
	ds_read_b128 v[164:167], v64 offset:4096
	ds_read_b128 v[168:171], v64 offset:6144
	v_mfma_f32_16x16x32_bf16 v[44:47], v[116:119], v[84:87], v[44:47]
	ds_read_b128 v[172:175], v67 offset:0
	ds_read_b128 v[176:179], v67 offset:2048
	ds_read_b128 v[188:191], v65 offset:0
	v_mfma_f32_16x16x32_bf16 v[36:39], v[116:119], v[88:91], v[36:39]
	ds_read_b128 v[192:195], v65 offset:2048
	ds_read_b128 v[196:199], v65 offset:4096
	ds_read_b128 v[200:203], v65 offset:6144
	s_waitcnt lgkmcnt(0)
	s_barrier
	v_mfma_f32_16x16x32_bf16 v[60:63], v[140:143], v[156:159], v[60:63]
	v_mfma_f32_16x16x32_bf16 v[68:71], v[140:143], v[160:163], v[68:71]
	s_add_u32 m0, s4, 0x0
	s_nop 0
	global_load_lds_dwordx4 v56, s[0:1]
	v_mfma_f32_16x16x32_bf16 v[52:55], v[140:143], v[164:167], v[52:55]
	v_mfma_f32_16x16x32_bf16 v[40:43], v[140:143], v[168:171], v[40:43]
	s_add_u32 m0, s4, 0x1000
	s_nop 0
	global_load_lds_dwordx4 v57, s[0:1]
	v_mfma_f32_16x16x32_bf16 v[72:75], v[144:147], v[156:159], v[72:75]
	v_mfma_f32_16x16x32_bf16 v[48:51], v[144:147], v[160:163], v[48:51]
	s_add_u32 m0, s4, 0x2000
	s_nop 0
	global_load_lds_dwordx4 v58, s[0:1]
	v_mfma_f32_16x16x32_bf16 v[44:47], v[144:147], v[164:167], v[44:47]
	v_mfma_f32_16x16x32_bf16 v[36:39], v[144:147], v[168:171], v[36:39]
	s_add_u32 m0, s4, 0x3000
	s_nop 0
	global_load_lds_dwordx4 v59, s[0:1]
	v_mfma_f32_16x16x32_bf16 v[60:63], v[172:175], v[188:191], v[60:63]
	v_mfma_f32_16x16x32_bf16 v[68:71], v[172:175], v[192:195], v[68:71]
	s_add_u32 m0, s4, 0x4000
	s_nop 0
	global_load_lds_dwordx4 v56, s[2:3]
	v_mfma_f32_16x16x32_bf16 v[52:55], v[172:175], v[196:199], v[52:55]
	v_mfma_f32_16x16x32_bf16 v[40:43], v[172:175], v[200:203], v[40:43]
	s_add_u32 s0, s0, 0x80
	s_addc_u32 s1, s1, 0
	s_add_u32 s2, s2, 0x80
	s_addc_u32 s3, s3, 0
	s_waitcnt vmcnt(5)
	s_barrier
	v_mfma_f32_16x16x32_bf16 v[72:75], v[176:179], v[188:191], v[72:75]
	ds_read_b128 v[220:223], v66 offset:32768
	ds_read_b128 v[224:227], v66 offset:34816
	ds_read_b128 v[236:239], v64 offset:32768
	v_mfma_f32_16x16x32_bf16 v[48:51], v[176:179], v[192:195], v[48:51]
	ds_read_b128 v[240:243], v64 offset:34816
	ds_read_b128 v[244:247], v64 offset:36864
	ds_read_b128 v[248:251], v64 offset:38912
	v_mfma_f32_16x16x32_bf16 v[44:47], v[176:179], v[196:199], v[44:47]
	ds_read_b128 v[112:115], v67 offset:32768
	ds_read_b128 v[116:119], v67 offset:34816
	ds_read_b128 v[76:79], v65 offset:32768
	v_mfma_f32_16x16x32_bf16 v[36:39], v[176:179], v[200:203], v[36:39]
	ds_read_b128 v[80:83], v65 offset:34816
	ds_read_b128 v[84:87], v65 offset:36864
	ds_read_b128 v[88:91], v65 offset:38912
	s_waitcnt lgkmcnt(0)
	s_barrier
	v_mfma_f32_16x16x32_bf16 v[60:63], v[220:223], v[236:239], v[60:63]
	v_mfma_f32_16x16x32_bf16 v[68:71], v[220:223], v[240:243], v[68:71]
	s_add_u32 m0, s4, 0x8000
	s_nop 0
	global_load_lds_dwordx4 v56, s[0:1]
	v_mfma_f32_16x16x32_bf16 v[52:55], v[220:223], v[244:247], v[52:55]
	v_mfma_f32_16x16x32_bf16 v[40:43], v[220:223], v[248:251], v[40:43]
	s_add_u32 m0, s4, 0x9000
	s_nop 0
	global_load_lds_dwordx4 v57, s[0:1]
	v_mfma_f32_16x16x32_bf16 v[72:75], v[224:227], v[236:239], v[72:75]
	v_mfma_f32_16x16x32_bf16 v[48:51], v[224:227], v[240:243], v[48:51]
	s_add_u32 m0, s4, 0xa000
	s_nop 0
	global_load_lds_dwordx4 v58, s[0:1]
	v_mfma_f32_16x16x32_bf16 v[44:47], v[224:227], v[244:247], v[44:47]
	v_mfma_f32_16x16x32_bf16 v[36:39], v[224:227], v[248:251], v[36:39]
	s_add_u32 m0, s4, 0xb000
	s_nop 0
	global_load_lds_dwordx4 v59, s[0:1]
	v_mfma_f32_16x16x32_bf16 v[60:63], v[112:115], v[76:79], v[60:63]
	v_mfma_f32_16x16x32_bf16 v[68:71], v[112:115], v[80:83], v[68:71]
	s_add_u32 m0, s4, 0xc000
	s_nop 0
	global_load_lds_dwordx4 v56, s[2:3]
	v_mfma_f32_16x16x32_bf16 v[52:55], v[112:115], v[84:87], v[52:55]
	v_mfma_f32_16x16x32_bf16 v[40:43], v[112:115], v[88:91], v[40:43]
	s_add_u32 s0, s0, 0x80
	s_addc_u32 s1, s1, 0
	s_add_u32 s2, s2, 0x80
	s_addc_u32 s3, s3, 0
	s_waitcnt vmcnt(5)
	s_barrier
	v_mfma_f32_16x16x32_bf16 v[72:75], v[116:119], v[76:79], v[72:75]
	ds_read_b128 v[140:143], v66 offset:0
	ds_read_b128 v[144:147], v66 offset:2048
	ds_read_b128 v[156:159], v64 offset:0
	v_mfma_f32_16x16x32_bf16 v[48:51], v[116:119], v[80:83], v[48:51]
	ds_read_b128 v[160:163], v64 offset:2048
	ds_read_b128 v[164:167], v64 offset:4096
	ds_read_b128 v[168:171], v64 offset:6144
	v_mfma_f32_16x16x32_bf16 v[44:47], v[116:119], v[84:87], v[44:47]
	ds_read_b128 v[172:175], v67 offset:0
	ds_read_b128 v[176:179], v67 offset:2048
	ds_read_b128 v[188:191], v65 offset:0
	v_mfma_f32_16x16x32_bf16 v[36:39], v[116:119], v[88:91], v[36:39]
	ds_read_b128 v[192:195], v65 offset:2048
	ds_read_b128 v[196:199], v65 offset:4096
	ds_read_b128 v[200:203], v65 offset:6144
	s_waitcnt lgkmcnt(0)
	s_barrier
	v_mfma_f32_16x16x32_bf16 v[60:63], v[140:143], v[156:159], v[60:63]
	v_mfma_f32_16x16x32_bf16 v[68:71], v[140:143], v[160:163], v[68:71]
	s_add_u32 m0, s4, 0x0
	s_nop 0
	global_load_lds_dwordx4 v56, s[0:1]
	v_mfma_f32_16x16x32_bf16 v[52:55], v[140:143], v[164:167], v[52:55]
	v_mfma_f32_16x16x32_bf16 v[40:43], v[140:143], v[168:171], v[40:43]
	s_add_u32 m0, s4, 0x1000
	s_nop 0
	global_load_lds_dwordx4 v57, s[0:1]
	v_mfma_f32_16x16x32_bf16 v[72:75], v[144:147], v[156:159], v[72:75]
	v_mfma_f32_16x16x32_bf16 v[48:51], v[144:147], v[160:163], v[48:51]
	s_add_u32 m0, s4, 0x2000
	s_nop 0
	global_load_lds_dwordx4 v58, s[0:1]
	v_mfma_f32_16x16x32_bf16 v[44:47], v[144:147], v[164:167], v[44:47]
	v_mfma_f32_16x16x32_bf16 v[36:39], v[144:147], v[168:171], v[36:39]
	s_add_u32 m0, s4, 0x3000
	s_nop 0
	global_load_lds_dwordx4 v59, s[0:1]
	v_mfma_f32_16x16x32_bf16 v[60:63], v[172:175], v[188:191], v[60:63]
	v_mfma_f32_16x16x32_bf16 v[68:71], v[172:175], v[192:195], v[68:71]
	s_add_u32 m0, s4, 0x4000
	s_nop 0
	global_load_lds_dwordx4 v56, s[2:3]
	v_mfma_f32_16x16x32_bf16 v[52:55], v[172:175], v[196:199], v[52:55]
	v_mfma_f32_16x16x32_bf16 v[40:43], v[172:175], v[200:203], v[40:43]
	s_add_u32 s0, s0, 0x80
	s_addc_u32 s1, s1, 0
	s_add_u32 s2, s2, 0x80
	s_addc_u32 s3, s3, 0
	s_waitcnt vmcnt(5)
	s_barrier
	v_mfma_f32_16x16x32_bf16 v[72:75], v[176:179], v[188:191], v[72:75]
	ds_read_b128 v[220:223], v66 offset:32768
	ds_read_b128 v[224:227], v66 offset:34816
	ds_read_b128 v[236:239], v64 offset:32768
	v_mfma_f32_16x16x32_bf16 v[48:51], v[176:179], v[192:195], v[48:51]
	ds_read_b128 v[240:243], v64 offset:34816
	ds_read_b128 v[244:247], v64 offset:36864
	ds_read_b128 v[248:251], v64 offset:38912
	v_mfma_f32_16x16x32_bf16 v[44:47], v[176:179], v[196:199], v[44:47]
	ds_read_b128 v[112:115], v67 offset:32768
	ds_read_b128 v[116:119], v67 offset:34816
	ds_read_b128 v[76:79], v65 offset:32768
	v_mfma_f32_16x16x32_bf16 v[36:39], v[176:179], v[200:203], v[36:39]
	ds_read_b128 v[80:83], v65 offset:34816
	ds_read_b128 v[84:87], v65 offset:36864
	ds_read_b128 v[88:91], v65 offset:38912
	s_waitcnt lgkmcnt(0)
	s_barrier
	v_mfma_f32_16x16x32_bf16 v[60:63], v[220:223], v[236:239], v[60:63]
	v_mfma_f32_16x16x32_bf16 v[68:71], v[220:223], v[240:243], v[68:71]
	s_add_u32 m0, s4, 0x8000
	s_nop 0
	global_load_lds_dwordx4 v56, s[0:1]
	v_mfma_f32_16x16x32_bf16 v[52:55], v[220:223], v[244:247], v[52:55]
	v_mfma_f32_16x16x32_bf16 v[40:43], v[220:223], v[248:251], v[40:43]
	s_add_u32 m0, s4, 0x9000
	s_nop 0
	global_load_lds_dwordx4 v57, s[0:1]
	v_mfma_f32_16x16x32_bf16 v[72:75], v[224:227], v[236:239], v[72:75]
	v_mfma_f32_16x16x32_bf16 v[48:51], v[224:227], v[240:243], v[48:51]
	s_add_u32 m0, s4, 0xa000
	s_nop 0
	global_load_lds_dwordx4 v58, s[0:1]
	v_mfma_f32_16x16x32_bf16 v[44:47], v[224:227], v[244:247], v[44:47]
	v_mfma_f32_16x16x32_bf16 v[36:39], v[224:227], v[248:251], v[36:39]
	s_add_u32 m0, s4, 0xb000
	s_nop 0
	global_load_lds_dwordx4 v59, s[0:1]
	v_mfma_f32_16x16x32_bf16 v[60:63], v[112:115], v[76:79], v[60:63]
	v_mfma_f32_16x16x32_bf16 v[68:71], v[112:115], v[80:83], v[68:71]
	s_add_u32 m0, s4, 0xc000
	s_nop 0
	global_load_lds_dwordx4 v56, s[2:3]
	v_mfma_f32_16x16x32_bf16 v[52:55], v[112:115], v[84:87], v[52:55]
	v_mfma_f32_16x16x32_bf16 v[40:43], v[112:115], v[88:91], v[40:43]
	s_add_u32 s0, s0, 0x80
	s_addc_u32 s1, s1, 0
	s_add_u32 s2, s2, 0x80
	s_addc_u32 s3, s3, 0
	s_waitcnt vmcnt(5)
	s_barrier
	v_mfma_f32_16x16x32_bf16 v[72:75], v[116:119], v[76:79], v[72:75]
	ds_read_b128 v[140:143], v66 offset:0
	ds_read_b128 v[144:147], v66 offset:2048
	ds_read_b128 v[156:159], v64 offset:0
	v_mfma_f32_16x16x32_bf16 v[48:51], v[116:119], v[80:83], v[48:51]
	ds_read_b128 v[160:163], v64 offset:2048
	ds_read_b128 v[164:167], v64 offset:4096
	ds_read_b128 v[168:171], v64 offset:6144
	v_mfma_f32_16x16x32_bf16 v[44:47], v[116:119], v[84:87], v[44:47]
	ds_read_b128 v[172:175], v67 offset:0
	ds_read_b128 v[176:179], v67 offset:2048
	ds_read_b128 v[188:191], v65 offset:0
	v_mfma_f32_16x16x32_bf16 v[36:39], v[116:119], v[88:91], v[36:39]
	ds_read_b128 v[192:195], v65 offset:2048
	ds_read_b128 v[196:199], v65 offset:4096
	ds_read_b128 v[200:203], v65 offset:6144
	s_waitcnt lgkmcnt(0)
	s_barrier
	v_mfma_f32_16x16x32_bf16 v[60:63], v[140:143], v[156:159], v[60:63]
	v_mfma_f32_16x16x32_bf16 v[68:71], v[140:143], v[160:163], v[68:71]
	s_add_u32 m0, s4, 0x0
	s_nop 0
	global_load_lds_dwordx4 v56, s[0:1]
	v_mfma_f32_16x16x32_bf16 v[52:55], v[140:143], v[164:167], v[52:55]
	v_mfma_f32_16x16x32_bf16 v[40:43], v[140:143], v[168:171], v[40:43]
	s_add_u32 m0, s4, 0x1000
	s_nop 0
	global_load_lds_dwordx4 v57, s[0:1]
	v_mfma_f32_16x16x32_bf16 v[72:75], v[144:147], v[156:159], v[72:75]
	v_mfma_f32_16x16x32_bf16 v[48:51], v[144:147], v[160:163], v[48:51]
	s_add_u32 m0, s4, 0x2000
	s_nop 0
	global_load_lds_dwordx4 v58, s[0:1]
	v_mfma_f32_16x16x32_bf16 v[44:47], v[144:147], v[164:167], v[44:47]
	v_mfma_f32_16x16x32_bf16 v[36:39], v[144:147], v[168:171], v[36:39]
	s_add_u32 m0, s4, 0x3000
	s_nop 0
	global_load_lds_dwordx4 v59, s[0:1]
	v_mfma_f32_16x16x32_bf16 v[60:63], v[172:175], v[188:191], v[60:63]
	v_mfma_f32_16x16x32_bf16 v[68:71], v[172:175], v[192:195], v[68:71]
	s_add_u32 m0, s4, 0x4000
	s_nop 0
	global_load_lds_dwordx4 v56, s[2:3]
	v_mfma_f32_16x16x32_bf16 v[52:55], v[172:175], v[196:199], v[52:55]
	v_mfma_f32_16x16x32_bf16 v[40:43], v[172:175], v[200:203], v[40:43]
	s_add_u32 s0, s0, 0x80
	s_addc_u32 s1, s1, 0
	s_add_u32 s2, s2, 0x80
	s_addc_u32 s3, s3, 0
	s_waitcnt vmcnt(5)
	s_barrier
	v_mfma_f32_16x16x32_bf16 v[72:75], v[176:179], v[188:191], v[72:75]
	ds_read_b128 v[220:223], v66 offset:32768
	ds_read_b128 v[224:227], v66 offset:34816
	ds_read_b128 v[236:239], v64 offset:32768
	v_mfma_f32_16x16x32_bf16 v[48:51], v[176:179], v[192:195], v[48:51]
	ds_read_b128 v[240:243], v64 offset:34816
	ds_read_b128 v[244:247], v64 offset:36864
	ds_read_b128 v[248:251], v64 offset:38912
	v_mfma_f32_16x16x32_bf16 v[44:47], v[176:179], v[196:199], v[44:47]
	ds_read_b128 v[112:115], v67 offset:32768
	ds_read_b128 v[116:119], v67 offset:34816
	ds_read_b128 v[76:79], v65 offset:32768
	v_mfma_f32_16x16x32_bf16 v[36:39], v[176:179], v[200:203], v[36:39]
	ds_read_b128 v[80:83], v65 offset:34816
	ds_read_b128 v[84:87], v65 offset:36864
	ds_read_b128 v[88:91], v65 offset:38912
	s_waitcnt lgkmcnt(0)
	s_barrier
	v_mfma_f32_16x16x32_bf16 v[60:63], v[220:223], v[236:239], v[60:63]
	v_mfma_f32_16x16x32_bf16 v[68:71], v[220:223], v[240:243], v[68:71]
	s_add_u32 m0, s4, 0x8000
	s_nop 0
	global_load_lds_dwordx4 v56, s[0:1]
	v_mfma_f32_16x16x32_bf16 v[52:55], v[220:223], v[244:247], v[52:55]
	v_mfma_f32_16x16x32_bf16 v[40:43], v[220:223], v[248:251], v[40:43]
	s_add_u32 m0, s4, 0x9000
	s_nop 0
	global_load_lds_dwordx4 v57, s[0:1]
	v_mfma_f32_16x16x32_bf16 v[72:75], v[224:227], v[236:239], v[72:75]
	v_mfma_f32_16x16x32_bf16 v[48:51], v[224:227], v[240:243], v[48:51]
	s_add_u32 m0, s4, 0xa000
	s_nop 0
	global_load_lds_dwordx4 v58, s[0:1]
	v_mfma_f32_16x16x32_bf16 v[44:47], v[224:227], v[244:247], v[44:47]
	v_mfma_f32_16x16x32_bf16 v[36:39], v[224:227], v[248:251], v[36:39]
	s_add_u32 m0, s4, 0xb000
	s_nop 0
	global_load_lds_dwordx4 v59, s[0:1]
	v_mfma_f32_16x16x32_bf16 v[60:63], v[112:115], v[76:79], v[60:63]
	v_mfma_f32_16x16x32_bf16 v[68:71], v[112:115], v[80:83], v[68:71]
	s_add_u32 m0, s4, 0xc000
	s_nop 0
	global_load_lds_dwordx4 v56, s[2:3]
	v_mfma_f32_16x16x32_bf16 v[52:55], v[112:115], v[84:87], v[52:55]
	v_mfma_f32_16x16x32_bf16 v[40:43], v[112:115], v[88:91], v[40:43]
	s_add_u32 s0, s0, 0x80
	s_addc_u32 s1, s1, 0
	s_add_u32 s2, s2, 0x80
	s_addc_u32 s3, s3, 0
	s_waitcnt vmcnt(5)
	s_barrier
	v_mfma_f32_16x16x32_bf16 v[72:75], v[116:119], v[76:79], v[72:75]
	ds_read_b128 v[140:143], v66 offset:0
	ds_read_b128 v[144:147], v66 offset:2048
	ds_read_b128 v[156:159], v64 offset:0
	v_mfma_f32_16x16x32_bf16 v[48:51], v[116:119], v[80:83], v[48:51]
	ds_read_b128 v[160:163], v64 offset:2048
	ds_read_b128 v[164:167], v64 offset:4096
	ds_read_b128 v[168:171], v64 offset:6144
	v_mfma_f32_16x16x32_bf16 v[44:47], v[116:119], v[84:87], v[44:47]
	ds_read_b128 v[172:175], v67 offset:0
	ds_read_b128 v[176:179], v67 offset:2048
	ds_read_b128 v[188:191], v65 offset:0
	v_mfma_f32_16x16x32_bf16 v[36:39], v[116:119], v[88:91], v[36:39]
	ds_read_b128 v[192:195], v65 offset:2048
	ds_read_b128 v[196:199], v65 offset:4096
	ds_read_b128 v[200:203], v65 offset:6144
	s_waitcnt lgkmcnt(0)
	s_barrier
	v_mfma_f32_16x16x32_bf16 v[60:63], v[140:143], v[156:159], v[60:63]
	v_mfma_f32_16x16x32_bf16 v[68:71], v[140:143], v[160:163], v[68:71]
	s_add_u32 m0, s4, 0x0
	s_nop 0
	global_load_lds_dwordx4 v56, s[0:1]
	v_mfma_f32_16x16x32_bf16 v[52:55], v[140:143], v[164:167], v[52:55]
	v_mfma_f32_16x16x32_bf16 v[40:43], v[140:143], v[168:171], v[40:43]
	s_add_u32 m0, s4, 0x1000
	s_nop 0
	global_load_lds_dwordx4 v57, s[0:1]
	v_mfma_f32_16x16x32_bf16 v[72:75], v[144:147], v[156:159], v[72:75]
	v_mfma_f32_16x16x32_bf16 v[48:51], v[144:147], v[160:163], v[48:51]
	s_add_u32 m0, s4, 0x2000
	s_nop 0
	global_load_lds_dwordx4 v58, s[0:1]
	v_mfma_f32_16x16x32_bf16 v[44:47], v[144:147], v[164:167], v[44:47]
	v_mfma_f32_16x16x32_bf16 v[36:39], v[144:147], v[168:171], v[36:39]
	s_add_u32 m0, s4, 0x3000
	s_nop 0
	global_load_lds_dwordx4 v59, s[0:1]
	v_mfma_f32_16x16x32_bf16 v[60:63], v[172:175], v[188:191], v[60:63]
	v_mfma_f32_16x16x32_bf16 v[68:71], v[172:175], v[192:195], v[68:71]
	s_add_u32 m0, s4, 0x4000
	s_nop 0
	global_load_lds_dwordx4 v56, s[2:3]
	v_mfma_f32_16x16x32_bf16 v[52:55], v[172:175], v[196:199], v[52:55]
	v_mfma_f32_16x16x32_bf16 v[40:43], v[172:175], v[200:203], v[40:43]
	s_add_u32 s0, s0, 0x80
	s_addc_u32 s1, s1, 0
	s_add_u32 s2, s2, 0x80
	s_addc_u32 s3, s3, 0
	s_waitcnt vmcnt(5)
	s_barrier
	v_mfma_f32_16x16x32_bf16 v[72:75], v[176:179], v[188:191], v[72:75]
	ds_read_b128 v[220:223], v66 offset:32768
	ds_read_b128 v[224:227], v66 offset:34816
	ds_read_b128 v[236:239], v64 offset:32768
	v_mfma_f32_16x16x32_bf16 v[48:51], v[176:179], v[192:195], v[48:51]
	ds_read_b128 v[240:243], v64 offset:34816
	ds_read_b128 v[244:247], v64 offset:36864
	ds_read_b128 v[248:251], v64 offset:38912
	v_mfma_f32_16x16x32_bf16 v[44:47], v[176:179], v[196:199], v[44:47]
	ds_read_b128 v[112:115], v67 offset:32768
	ds_read_b128 v[116:119], v67 offset:34816
	ds_read_b128 v[76:79], v65 offset:32768
	v_mfma_f32_16x16x32_bf16 v[36:39], v[176:179], v[200:203], v[36:39]
	ds_read_b128 v[80:83], v65 offset:34816
	ds_read_b128 v[84:87], v65 offset:36864
	ds_read_b128 v[88:91], v65 offset:38912
	s_waitcnt lgkmcnt(0)
	s_barrier
	v_mfma_f32_16x16x32_bf16 v[60:63], v[220:223], v[236:239], v[60:63]
	v_mfma_f32_16x16x32_bf16 v[68:71], v[220:223], v[240:243], v[68:71]
	s_add_u32 m0, s4, 0x8000
	s_nop 0
	global_load_lds_dwordx4 v56, s[0:1]
	v_mfma_f32_16x16x32_bf16 v[52:55], v[220:223], v[244:247], v[52:55]
	v_mfma_f32_16x16x32_bf16 v[40:43], v[220:223], v[248:251], v[40:43]
	s_add_u32 m0, s4, 0x9000
	s_nop 0
	global_load_lds_dwordx4 v57, s[0:1]
	v_mfma_f32_16x16x32_bf16 v[72:75], v[224:227], v[236:239], v[72:75]
	v_mfma_f32_16x16x32_bf16 v[48:51], v[224:227], v[240:243], v[48:51]
	s_add_u32 m0, s4, 0xa000
	s_nop 0
	global_load_lds_dwordx4 v58, s[0:1]
	v_mfma_f32_16x16x32_bf16 v[44:47], v[224:227], v[244:247], v[44:47]
	v_mfma_f32_16x16x32_bf16 v[36:39], v[224:227], v[248:251], v[36:39]
	s_add_u32 m0, s4, 0xb000
	s_nop 0
	global_load_lds_dwordx4 v59, s[0:1]
	v_mfma_f32_16x16x32_bf16 v[60:63], v[112:115], v[76:79], v[60:63]
	v_mfma_f32_16x16x32_bf16 v[68:71], v[112:115], v[80:83], v[68:71]
	s_add_u32 m0, s4, 0xc000
	s_nop 0
	global_load_lds_dwordx4 v56, s[2:3]
	v_mfma_f32_16x16x32_bf16 v[52:55], v[112:115], v[84:87], v[52:55]
	v_mfma_f32_16x16x32_bf16 v[40:43], v[112:115], v[88:91], v[40:43]
	s_add_u32 s0, s0, 0x80
	s_addc_u32 s1, s1, 0
	s_add_u32 s2, s2, 0x80
	s_addc_u32 s3, s3, 0
	s_waitcnt vmcnt(5)
	s_barrier
	v_mfma_f32_16x16x32_bf16 v[72:75], v[116:119], v[76:79], v[72:75]
	ds_read_b128 v[140:143], v66 offset:0
	ds_read_b128 v[144:147], v66 offset:2048
	ds_read_b128 v[156:159], v64 offset:0
	v_mfma_f32_16x16x32_bf16 v[48:51], v[116:119], v[80:83], v[48:51]
	ds_read_b128 v[160:163], v64 offset:2048
	ds_read_b128 v[164:167], v64 offset:4096
	ds_read_b128 v[168:171], v64 offset:6144
	v_mfma_f32_16x16x32_bf16 v[44:47], v[116:119], v[84:87], v[44:47]
	ds_read_b128 v[172:175], v67 offset:0
	ds_read_b128 v[176:179], v67 offset:2048
	ds_read_b128 v[188:191], v65 offset:0
	v_mfma_f32_16x16x32_bf16 v[36:39], v[116:119], v[88:91], v[36:39]
	ds_read_b128 v[192:195], v65 offset:2048
	ds_read_b128 v[196:199], v65 offset:4096
	ds_read_b128 v[200:203], v65 offset:6144
	s_waitcnt lgkmcnt(0)
	s_barrier
	v_mfma_f32_16x16x32_bf16 v[60:63], v[140:143], v[156:159], v[60:63]
	v_mfma_f32_16x16x32_bf16 v[68:71], v[140:143], v[160:163], v[68:71]
	s_add_u32 m0, s4, 0x0
	s_nop 0
	global_load_lds_dwordx4 v56, s[0:1]
	v_mfma_f32_16x16x32_bf16 v[52:55], v[140:143], v[164:167], v[52:55]
	v_mfma_f32_16x16x32_bf16 v[40:43], v[140:143], v[168:171], v[40:43]
	s_add_u32 m0, s4, 0x1000
	s_nop 0
	global_load_lds_dwordx4 v57, s[0:1]
	v_mfma_f32_16x16x32_bf16 v[72:75], v[144:147], v[156:159], v[72:75]
	v_mfma_f32_16x16x32_bf16 v[48:51], v[144:147], v[160:163], v[48:51]
	s_add_u32 m0, s4, 0x2000
	s_nop 0
	global_load_lds_dwordx4 v58, s[0:1]
	v_mfma_f32_16x16x32_bf16 v[44:47], v[144:147], v[164:167], v[44:47]
	v_mfma_f32_16x16x32_bf16 v[36:39], v[144:147], v[168:171], v[36:39]
	s_add_u32 m0, s4, 0x3000
	s_nop 0
	global_load_lds_dwordx4 v59, s[0:1]
	v_mfma_f32_16x16x32_bf16 v[60:63], v[172:175], v[188:191], v[60:63]
	v_mfma_f32_16x16x32_bf16 v[68:71], v[172:175], v[192:195], v[68:71]
	s_add_u32 m0, s4, 0x4000
	s_nop 0
	global_load_lds_dwordx4 v56, s[2:3]
	v_mfma_f32_16x16x32_bf16 v[52:55], v[172:175], v[196:199], v[52:55]
	v_mfma_f32_16x16x32_bf16 v[40:43], v[172:175], v[200:203], v[40:43]
	s_add_u32 s0, s0, 0x80
	s_addc_u32 s1, s1, 0
	s_add_u32 s2, s2, 0x80
	s_addc_u32 s3, s3, 0
	s_waitcnt vmcnt(5)
	s_barrier
	v_mfma_f32_16x16x32_bf16 v[72:75], v[176:179], v[188:191], v[72:75]
	ds_read_b128 v[220:223], v66 offset:32768
	ds_read_b128 v[224:227], v66 offset:34816
	ds_read_b128 v[236:239], v64 offset:32768
	v_mfma_f32_16x16x32_bf16 v[48:51], v[176:179], v[192:195], v[48:51]
	ds_read_b128 v[240:243], v64 offset:34816
	ds_read_b128 v[244:247], v64 offset:36864
	ds_read_b128 v[248:251], v64 offset:38912
	v_mfma_f32_16x16x32_bf16 v[44:47], v[176:179], v[196:199], v[44:47]
	ds_read_b128 v[112:115], v67 offset:32768
	ds_read_b128 v[116:119], v67 offset:34816
	ds_read_b128 v[76:79], v65 offset:32768
	v_mfma_f32_16x16x32_bf16 v[36:39], v[176:179], v[200:203], v[36:39]
	ds_read_b128 v[80:83], v65 offset:34816
	ds_read_b128 v[84:87], v65 offset:36864
	ds_read_b128 v[88:91], v65 offset:38912
	s_waitcnt lgkmcnt(0)
	s_barrier
	v_mfma_f32_16x16x32_bf16 v[60:63], v[220:223], v[236:239], v[60:63]
	v_mfma_f32_16x16x32_bf16 v[68:71], v[220:223], v[240:243], v[68:71]
	s_add_u32 m0, s4, 0x8000
	s_nop 0
	global_load_lds_dwordx4 v56, s[0:1]
	v_mfma_f32_16x16x32_bf16 v[52:55], v[220:223], v[244:247], v[52:55]
	v_mfma_f32_16x16x32_bf16 v[40:43], v[220:223], v[248:251], v[40:43]
	s_add_u32 m0, s4, 0x9000
	s_nop 0
	global_load_lds_dwordx4 v57, s[0:1]
	v_mfma_f32_16x16x32_bf16 v[72:75], v[224:227], v[236:239], v[72:75]
	v_mfma_f32_16x16x32_bf16 v[48:51], v[224:227], v[240:243], v[48:51]
	s_add_u32 m0, s4, 0xa000
	s_nop 0
	global_load_lds_dwordx4 v58, s[0:1]
	v_mfma_f32_16x16x32_bf16 v[44:47], v[224:227], v[244:247], v[44:47]
	v_mfma_f32_16x16x32_bf16 v[36:39], v[224:227], v[248:251], v[36:39]
	s_add_u32 m0, s4, 0xb000
	s_nop 0
	global_load_lds_dwordx4 v59, s[0:1]
	v_mfma_f32_16x16x32_bf16 v[60:63], v[112:115], v[76:79], v[60:63]
	v_mfma_f32_16x16x32_bf16 v[68:71], v[112:115], v[80:83], v[68:71]
	s_add_u32 m0, s4, 0xc000
	s_nop 0
	global_load_lds_dwordx4 v56, s[2:3]
	v_mfma_f32_16x16x32_bf16 v[52:55], v[112:115], v[84:87], v[52:55]
	v_mfma_f32_16x16x32_bf16 v[40:43], v[112:115], v[88:91], v[40:43]
	s_add_u32 s0, s0, 0x80
	s_addc_u32 s1, s1, 0
	s_add_u32 s2, s2, 0x80
	s_addc_u32 s3, s3, 0
	s_waitcnt vmcnt(5)
	s_barrier
	v_mfma_f32_16x16x32_bf16 v[72:75], v[116:119], v[76:79], v[72:75]
	ds_read_b128 v[140:143], v66 offset:0
	ds_read_b128 v[144:147], v66 offset:2048
	ds_read_b128 v[156:159], v64 offset:0
	v_mfma_f32_16x16x32_bf16 v[48:51], v[116:119], v[80:83], v[48:51]
	ds_read_b128 v[160:163], v64 offset:2048
	ds_read_b128 v[164:167], v64 offset:4096
	ds_read_b128 v[168:171], v64 offset:6144
	v_mfma_f32_16x16x32_bf16 v[44:47], v[116:119], v[84:87], v[44:47]
	ds_read_b128 v[172:175], v67 offset:0
	ds_read_b128 v[176:179], v67 offset:2048
	ds_read_b128 v[188:191], v65 offset:0
	v_mfma_f32_16x16x32_bf16 v[36:39], v[116:119], v[88:91], v[36:39]
	ds_read_b128 v[192:195], v65 offset:2048
	ds_read_b128 v[196:199], v65 offset:4096
	ds_read_b128 v[200:203], v65 offset:6144
	s_waitcnt lgkmcnt(0)
	s_barrier
	v_mfma_f32_16x16x32_bf16 v[60:63], v[140:143], v[156:159], v[60:63]
	v_mfma_f32_16x16x32_bf16 v[68:71], v[140:143], v[160:163], v[68:71]
	v_mfma_f32_16x16x32_bf16 v[52:55], v[140:143], v[164:167], v[52:55]
	v_mfma_f32_16x16x32_bf16 v[40:43], v[140:143], v[168:171], v[40:43]
	v_mfma_f32_16x16x32_bf16 v[72:75], v[144:147], v[156:159], v[72:75]
	v_mfma_f32_16x16x32_bf16 v[48:51], v[144:147], v[160:163], v[48:51]
	v_mfma_f32_16x16x32_bf16 v[44:47], v[144:147], v[164:167], v[44:47]
	v_mfma_f32_16x16x32_bf16 v[36:39], v[144:147], v[168:171], v[36:39]
	v_mfma_f32_16x16x32_bf16 v[60:63], v[172:175], v[188:191], v[60:63]
	v_mfma_f32_16x16x32_bf16 v[68:71], v[172:175], v[192:195], v[68:71]
	v_mfma_f32_16x16x32_bf16 v[52:55], v[172:175], v[196:199], v[52:55]
	v_mfma_f32_16x16x32_bf16 v[40:43], v[172:175], v[200:203], v[40:43]
	s_waitcnt vmcnt(0)
	s_barrier
	v_mfma_f32_16x16x32_bf16 v[72:75], v[176:179], v[188:191], v[72:75]
	ds_read_b128 v[220:223], v66 offset:32768
	ds_read_b128 v[224:227], v66 offset:34816
	ds_read_b128 v[236:239], v64 offset:32768
	v_mfma_f32_16x16x32_bf16 v[48:51], v[176:179], v[192:195], v[48:51]
	ds_read_b128 v[240:243], v64 offset:34816
	ds_read_b128 v[244:247], v64 offset:36864
	ds_read_b128 v[248:251], v64 offset:38912
	v_mfma_f32_16x16x32_bf16 v[44:47], v[176:179], v[196:199], v[44:47]
	ds_read_b128 v[112:115], v67 offset:32768
	ds_read_b128 v[116:119], v67 offset:34816
	ds_read_b128 v[76:79], v65 offset:32768
	v_mfma_f32_16x16x32_bf16 v[36:39], v[176:179], v[200:203], v[36:39]
	ds_read_b128 v[80:83], v65 offset:34816
	ds_read_b128 v[84:87], v65 offset:36864
	ds_read_b128 v[88:91], v65 offset:38912
	s_waitcnt lgkmcnt(0)
	s_barrier
	v_mfma_f32_16x16x32_bf16 v[60:63], v[220:223], v[236:239], v[60:63]
	v_mfma_f32_16x16x32_bf16 v[68:71], v[220:223], v[240:243], v[68:71]
	v_mfma_f32_16x16x32_bf16 v[52:55], v[220:223], v[244:247], v[52:55]
	v_mfma_f32_16x16x32_bf16 v[40:43], v[220:223], v[248:251], v[40:43]
	v_mfma_f32_16x16x32_bf16 v[72:75], v[224:227], v[236:239], v[72:75]
	v_mfma_f32_16x16x32_bf16 v[48:51], v[224:227], v[240:243], v[48:51]
	v_mfma_f32_16x16x32_bf16 v[44:47], v[224:227], v[244:247], v[44:47]
	v_mfma_f32_16x16x32_bf16 v[36:39], v[224:227], v[248:251], v[36:39]
	v_mfma_f32_16x16x32_bf16 v[60:63], v[112:115], v[76:79], v[60:63]
	v_mfma_f32_16x16x32_bf16 v[68:71], v[112:115], v[80:83], v[68:71]
	v_mfma_f32_16x16x32_bf16 v[52:55], v[112:115], v[84:87], v[52:55]
	v_mfma_f32_16x16x32_bf16 v[40:43], v[112:115], v[88:91], v[40:43]
	v_mfma_f32_16x16x32_bf16 v[72:75], v[116:119], v[76:79], v[72:75]
	v_mfma_f32_16x16x32_bf16 v[48:51], v[116:119], v[80:83], v[48:51]
	v_mfma_f32_16x16x32_bf16 v[44:47], v[116:119], v[84:87], v[44:47]
	v_mfma_f32_16x16x32_bf16 v[36:39], v[116:119], v[88:91], v[36:39]
